# PV ring 8th slot moved to idle QK ring registers so the running row sum stays in v232 (no per-tile copy); g1 per-tile canonicalising max removed
# baseline (speedup 1.0000x reference)
.LBB0_517:
	v_fmamk_f32 v144, v144, 0x3e0293ee, v237
	v_fmamk_f32 v145, v145, 0x3e0293ee, v237
	v_fmamk_f32 v146, v146, 0x3e0293ee, v237
	v_fmamk_f32 v147, v147, 0x3e0293ee, v237
	v_fmamk_f32 v148, v148, 0x3e0293ee, v237
	v_fmamk_f32 v149, v149, 0x3e0293ee, v237
	v_fmamk_f32 v150, v150, 0x3e0293ee, v237
	v_fmamk_f32 v151, v151, 0x3e0293ee, v237
	v_fmamk_f32 v152, v152, 0x3e0293ee, v237
	v_fmamk_f32 v153, v153, 0x3e0293ee, v237
	v_fmamk_f32 v154, v154, 0x3e0293ee, v237
	v_fmamk_f32 v155, v155, 0x3e0293ee, v237
	v_fmamk_f32 v156, v156, 0x3e0293ee, v237
	v_fmamk_f32 v157, v157, 0x3e0293ee, v237
	v_fmamk_f32 v158, v158, 0x3e0293ee, v237
	v_fmamk_f32 v159, v159, 0x3e0293ee, v237
	v_fmamk_f32 v128, v128, 0x3e0293ee, v237
	v_fmamk_f32 v129, v129, 0x3e0293ee, v237
	v_fmamk_f32 v130, v130, 0x3e0293ee, v237
	v_fmamk_f32 v131, v131, 0x3e0293ee, v237
	v_fmamk_f32 v132, v132, 0x3e0293ee, v237
	v_fmamk_f32 v133, v133, 0x3e0293ee, v237
	v_fmamk_f32 v134, v134, 0x3e0293ee, v237
	v_fmamk_f32 v135, v135, 0x3e0293ee, v237
	v_fmamk_f32 v136, v136, 0x3e0293ee, v237
	v_fmamk_f32 v137, v137, 0x3e0293ee, v237
	v_fmamk_f32 v138, v138, 0x3e0293ee, v237
	v_fmamk_f32 v139, v139, 0x3e0293ee, v237
	v_fmamk_f32 v140, v140, 0x3e0293ee, v237
	v_fmamk_f32 v141, v141, 0x3e0293ee, v237
	v_fmamk_f32 v142, v142, 0x3e0293ee, v237
	v_fmamk_f32 v192, v143, 0x3e0293ee, v237
	v_exp_f32_e32 v143, v144
	v_exp_f32_e32 v145, v145
	v_exp_f32_e32 v146, v146
	v_exp_f32_e32 v147, v147
	v_exp_f32_e32 v148, v148
	v_exp_f32_e32 v193, v128
	v_exp_f32_e32 v149, v149
	v_add_f32_e32 v128, v145, v143
	v_exp_f32_e32 v150, v150
	v_add_f32_e32 v128, v146, v128
	v_exp_f32_e32 v151, v151
	v_add_f32_e32 v128, v147, v128
	v_exp_f32_e32 v152, v152
	v_add_f32_e32 v128, v148, v128
	v_exp_f32_e32 v153, v153
	v_add_f32_e32 v128, v149, v128
	v_exp_f32_e32 v154, v154
	v_add_f32_e32 v128, v150, v128
	v_exp_f32_e32 v155, v155
	v_add_f32_e32 v128, v151, v128
	v_exp_f32_e32 v156, v156
	v_add_f32_e32 v128, v152, v128
	v_exp_f32_e32 v157, v157
	v_add_f32_e32 v128, v153, v128
	v_exp_f32_e32 v158, v158
	v_add_f32_e32 v128, v154, v128
	v_exp_f32_e32 v159, v159
	v_add_f32_e32 v128, v155, v128
	v_add_f32_e32 v128, v156, v128
	v_exp_f32_e32 v194, v129
	v_add_f32_e32 v128, v157, v128
	v_exp_f32_e32 v195, v130
	v_add_f32_e32 v128, v158, v128
	v_exp_f32_e32 v196, v131
	v_add_f32_e32 v128, v159, v128
	v_exp_f32_e32 v197, v132
	v_add_f32_e32 v128, v193, v128
	v_exp_f32_e32 v198, v133
	v_add_f32_e32 v128, v194, v128
	v_exp_f32_e32 v199, v134
	v_add_f32_e32 v128, v195, v128
	v_exp_f32_e32 v135, v135
	v_add_f32_e32 v128, v196, v128
	v_exp_f32_e32 v200, v136
	v_add_f32_e32 v128, v197, v128
	v_exp_f32_e32 v201, v137
	v_add_f32_e32 v128, v198, v128
	v_exp_f32_e32 v202, v138
	v_add_f32_e32 v128, v199, v128
	v_exp_f32_e32 v203, v139
	v_add_f32_e32 v128, v135, v128
	v_exp_f32_e32 v204, v140
	v_add_f32_e32 v128, v200, v128
	v_exp_f32_e32 v205, v141
	v_add_f32_e32 v128, v201, v128
	v_exp_f32_e32 v206, v142
	v_add_f32_e32 v128, v202, v128
	v_exp_f32_e32 v192, v192
	v_add_f32_e32 v128, v203, v128
	v_add_f32_e32 v128, v204, v128
	v_add_f32_e32 v128, v205, v128
	v_add_f32_e32 v128, v206, v128
	v_add_f32_e32 v128, v192, v128
	v_add_f32_e32 v232, v232, v128
	v_cvt_pk_bf16_f32 v128, v143, v145
	v_cvt_pk_bf16_f32 v129, v146, v147
	v_cvt_pk_bf16_f32 v130, v148, v149
	v_cvt_pk_bf16_f32 v131, v150, v151
	v_cvt_pk_bf16_f32 v136, v152, v153
	v_cvt_pk_bf16_f32 v137, v154, v155
	v_cvt_pk_bf16_f32 v138, v156, v157
	v_cvt_pk_bf16_f32 v139, v158, v159
	v_cvt_pk_bf16_f32 v132, v193, v194
	v_cvt_pk_bf16_f32 v133, v195, v196
	v_cvt_pk_bf16_f32 v134, v197, v198
	v_cvt_pk_bf16_f32 v135, v199, v135
	v_cvt_pk_bf16_f32 v140, v200, v201
	v_cvt_pk_bf16_f32 v141, v202, v203
	v_cvt_pk_bf16_f32 v142, v204, v205
	v_cvt_pk_bf16_f32 v143, v206, v192
	v_lshl_add_u32 v145, s76, 15, v230
	ds_read_b64_tr_b16 v[146:147], v145 offset:0
	ds_read_b64_tr_b16 v[148:149], v145 offset:4096
	ds_read_b64_tr_b16 v[150:151], v145 offset:512
	ds_read_b64_tr_b16 v[152:153], v145 offset:4608
	ds_read_b64_tr_b16 v[154:155], v145 offset:1024
	ds_read_b64_tr_b16 v[156:157], v145 offset:5120
	ds_read_b64_tr_b16 v[192:193], v145 offset:1536
	ds_read_b64_tr_b16 v[194:195], v145 offset:5632
	ds_read_b64_tr_b16 v[196:197], v145 offset:2048
	ds_read_b64_tr_b16 v[198:199], v145 offset:6144
	ds_read_b64_tr_b16 v[200:201], v145 offset:2560
	ds_read_b64_tr_b16 v[202:203], v145 offset:6656
	ds_read_b64_tr_b16 v[204:205], v145 offset:3072
	ds_read_b64_tr_b16 v[206:207], v145 offset:7168
	s_waitcnt lgkmcnt(12)
	s_nop 0
	v_mfma_f32_32x32x16_bf16 v[0:15], v[128:131], v[146:149], v[0:15]
	ds_read_b64_tr_b16 v[240:241], v145 offset:3584
	ds_read_b64_tr_b16 v[242:243], v145 offset:7680
	s_waitcnt lgkmcnt(12)
	v_mfma_f32_32x32x16_bf16 v[112:127], v[128:131], v[150:153], v[112:127]
	ds_read_b64_tr_b16 v[146:147], v145 offset:8192
	ds_read_b64_tr_b16 v[148:149], v145 offset:12288
	s_waitcnt lgkmcnt(12)
	v_mfma_f32_32x32x16_bf16 v[96:111], v[128:131], v[154:157], v[96:111]
	ds_read_b64_tr_b16 v[150:151], v145 offset:8704
	ds_read_b64_tr_b16 v[152:153], v145 offset:12800
	s_waitcnt lgkmcnt(12)
	v_mfma_f32_32x32x16_bf16 v[80:95], v[128:131], v[192:195], v[80:95]
	ds_read_b64_tr_b16 v[154:155], v145 offset:9216
	ds_read_b64_tr_b16 v[156:157], v145 offset:13312
	s_waitcnt lgkmcnt(12)
	v_mfma_f32_32x32x16_bf16 v[64:79], v[128:131], v[196:199], v[64:79]
	ds_read_b64_tr_b16 v[192:193], v145 offset:9728
	ds_read_b64_tr_b16 v[194:195], v145 offset:13824
	s_waitcnt lgkmcnt(12)
	v_mfma_f32_32x32x16_bf16 v[48:63], v[128:131], v[200:203], v[48:63]
	ds_read_b64_tr_b16 v[196:197], v145 offset:10240
	ds_read_b64_tr_b16 v[198:199], v145 offset:14336
	s_waitcnt lgkmcnt(12)
	v_mfma_f32_32x32x16_bf16 v[32:47], v[128:131], v[204:207], v[32:47]
	ds_read_b64_tr_b16 v[200:201], v145 offset:10752
	ds_read_b64_tr_b16 v[202:203], v145 offset:14848
	s_waitcnt lgkmcnt(12)
	v_mfma_f32_32x32x16_bf16 v[16:31], v[128:131], v[240:243], v[16:31]
	ds_read_b64_tr_b16 v[204:205], v145 offset:11264
	ds_read_b64_tr_b16 v[206:207], v145 offset:15360
	s_waitcnt lgkmcnt(12)
	v_mfma_f32_32x32x16_bf16 v[0:15], v[136:139], v[146:149], v[0:15]
	ds_read_b64_tr_b16 v[240:241], v145 offset:11776
	ds_read_b64_tr_b16 v[242:243], v145 offset:15872
	s_waitcnt lgkmcnt(12)
	v_mfma_f32_32x32x16_bf16 v[112:127], v[136:139], v[150:153], v[112:127]
	ds_read_b64_tr_b16 v[146:147], v145 offset:16384
	ds_read_b64_tr_b16 v[148:149], v145 offset:20480
	s_waitcnt lgkmcnt(12)
	v_mfma_f32_32x32x16_bf16 v[96:111], v[136:139], v[154:157], v[96:111]
	ds_read_b64_tr_b16 v[150:151], v145 offset:16896
	ds_read_b64_tr_b16 v[152:153], v145 offset:20992
	s_waitcnt lgkmcnt(12)
	v_mfma_f32_32x32x16_bf16 v[80:95], v[136:139], v[192:195], v[80:95]
	ds_read_b64_tr_b16 v[154:155], v145 offset:17408
	ds_read_b64_tr_b16 v[156:157], v145 offset:21504
	s_waitcnt lgkmcnt(12)
	v_mfma_f32_32x32x16_bf16 v[64:79], v[136:139], v[196:199], v[64:79]
	ds_read_b64_tr_b16 v[192:193], v145 offset:17920
	ds_read_b64_tr_b16 v[194:195], v145 offset:22016
	s_waitcnt lgkmcnt(12)
	v_mfma_f32_32x32x16_bf16 v[48:63], v[136:139], v[200:203], v[48:63]
	ds_read_b64_tr_b16 v[196:197], v145 offset:18432
	ds_read_b64_tr_b16 v[198:199], v145 offset:22528
	s_waitcnt lgkmcnt(12)
	v_mfma_f32_32x32x16_bf16 v[32:47], v[136:139], v[204:207], v[32:47]
	ds_read_b64_tr_b16 v[200:201], v145 offset:18944
	ds_read_b64_tr_b16 v[202:203], v145 offset:23040
	s_waitcnt lgkmcnt(12)
	v_mfma_f32_32x32x16_bf16 v[16:31], v[136:139], v[240:243], v[16:31]
	ds_read_b64_tr_b16 v[204:205], v145 offset:19456
	ds_read_b64_tr_b16 v[206:207], v145 offset:23552
	s_waitcnt lgkmcnt(12)
	v_mfma_f32_32x32x16_bf16 v[0:15], v[132:135], v[146:149], v[0:15]
	ds_read_b64_tr_b16 v[240:241], v145 offset:19968
	ds_read_b64_tr_b16 v[242:243], v145 offset:24064
	s_waitcnt lgkmcnt(12)
	v_mfma_f32_32x32x16_bf16 v[112:127], v[132:135], v[150:153], v[112:127]
	ds_read_b64_tr_b16 v[146:147], v145 offset:24576
	ds_read_b64_tr_b16 v[148:149], v145 offset:28672
	s_waitcnt lgkmcnt(12)
	v_mfma_f32_32x32x16_bf16 v[96:111], v[132:135], v[154:157], v[96:111]
	ds_read_b64_tr_b16 v[150:151], v145 offset:25088
	ds_read_b64_tr_b16 v[152:153], v145 offset:29184
	s_waitcnt lgkmcnt(12)
	v_mfma_f32_32x32x16_bf16 v[80:95], v[132:135], v[192:195], v[80:95]
	ds_read_b64_tr_b16 v[154:155], v145 offset:25600
	ds_read_b64_tr_b16 v[156:157], v145 offset:29696
	s_waitcnt lgkmcnt(12)
	v_mfma_f32_32x32x16_bf16 v[64:79], v[132:135], v[196:199], v[64:79]
	ds_read_b64_tr_b16 v[192:193], v145 offset:26112
	ds_read_b64_tr_b16 v[194:195], v145 offset:30208
	s_waitcnt lgkmcnt(12)
	v_mfma_f32_32x32x16_bf16 v[48:63], v[132:135], v[200:203], v[48:63]
	ds_read_b64_tr_b16 v[196:197], v145 offset:26624
	ds_read_b64_tr_b16 v[198:199], v145 offset:30720
	s_waitcnt lgkmcnt(12)
	v_mfma_f32_32x32x16_bf16 v[32:47], v[132:135], v[204:207], v[32:47]
	ds_read_b64_tr_b16 v[200:201], v145 offset:27136
	ds_read_b64_tr_b16 v[202:203], v145 offset:31232
	s_waitcnt lgkmcnt(12)
	v_mfma_f32_32x32x16_bf16 v[16:31], v[132:135], v[240:243], v[16:31]
	ds_read_b64_tr_b16 v[204:205], v145 offset:27648
	ds_read_b64_tr_b16 v[206:207], v145 offset:31744
	s_waitcnt lgkmcnt(12)
	v_mfma_f32_32x32x16_bf16 v[0:15], v[140:143], v[146:149], v[0:15]
	ds_read_b64_tr_b16 v[240:241], v145 offset:28160
	ds_read_b64_tr_b16 v[242:243], v145 offset:32256
	s_waitcnt lgkmcnt(12)
	v_mfma_f32_32x32x16_bf16 v[112:127], v[140:143], v[150:153], v[112:127]
	s_waitcnt lgkmcnt(10)
	v_mfma_f32_32x32x16_bf16 v[96:111], v[140:143], v[154:157], v[96:111]
	s_waitcnt lgkmcnt(8)
	v_mfma_f32_32x32x16_bf16 v[80:95], v[140:143], v[192:195], v[80:95]
	s_waitcnt lgkmcnt(6)
	v_mfma_f32_32x32x16_bf16 v[64:79], v[140:143], v[196:199], v[64:79]
	s_add_i32 s4, s76, 1
	s_cmp_lg_u32 s76, 2
	s_cselect_b32 s76, s4, 0
	s_add_i32 s4, s74, 1
	s_cmp_lg_u32 s74, 2
	s_cselect_b32 s74, s4, 0
	s_add_u32 s22, s22, 0x20000
	s_waitcnt lgkmcnt(4)
	v_mfma_f32_32x32x16_bf16 v[48:63], v[140:143], v[200:203], v[48:63]
	s_addc_u32 s23, s23, 0
	s_add_i32 s86, s86, 1
	s_cmp_eq_u32 s22, 0x800000
	s_waitcnt lgkmcnt(2)
	v_mfma_f32_32x32x16_bf16 v[32:47], v[140:143], v[204:207], v[32:47]
	s_waitcnt lgkmcnt(0)
	v_mfma_f32_32x32x16_bf16 v[16:31], v[140:143], v[240:243], v[16:31]
	s_cbranch_scc1 .LBB0_521
	s_cmp_eq_u32 s22, 0x7e0000
	s_mov_b64 s[4:5], -1
	s_cbranch_scc1 .LBB0_510

.LBB0_521:
	v_mov_b32_e32 v129, v232
	s_nop 1
	v_permlane32_swap_b32_e32 v232, v129
	v_add_f32_e32 v232, v232, v129
	s_and_saveexec_b64 s[4:5], s[0:1]
	ds_write_b32 v226, v232
	s_or_b64 exec, exec, s[4:5]
	s_waitcnt lgkmcnt(0)
	v_add_u32_e32 v136, s21, v210
	ds_read_b128 v[128:131], v136
	ds_read_b128 v[132:135], v136 offset:32
	s_ashr_i32 s21, s20, 31
	s_lshl_b64 s[0:1], s[20:21], 12
	ds_read_b128 v[138:141], v136 offset:96
	s_waitcnt lgkmcnt(2)
	v_rcp_f32_e32 v142, v128
	v_rcp_f32_e32 v145, v129
	v_rcp_f32_e32 v152, v130
	v_rcp_f32_e32 v161, v131
	ds_read_b128 v[128:131], v136 offset:64
	s_waitcnt lgkmcnt(2)
	v_rcp_f32_e32 v162, v132
	v_rcp_f32_e32 v163, v133
	v_rcp_f32_e32 v164, v134
	v_rcp_f32_e32 v165, v135
	s_waitcnt lgkmcnt(0)
	v_rcp_f32_e32 v137, v128
	v_rcp_f32_e32 v136, v129
	v_rcp_f32_e32 v135, v130
	v_rcp_f32_e32 v134, v131
	v_rcp_f32_e32 v133, v138
	v_rcp_f32_e32 v132, v139
	v_rcp_f32_e32 v131, v140
	v_rcp_f32_e32 v130, v141
	s_add_u32 s0, s62, s0
	s_addc_u32 s1, s63, s1
	s_mov_b64 s[4:5], -1
	s_andn2_b64 vcc, exec, s[18:19]
	v_lshlrev_b32_e32 v210, 2, v219
	v_lshlrev_b32_e32 v128, 14, v218
	v_lshl_add_u32 v129, v218, 5, v219
	v_lshlrev_b32_e32 v128, 4, v129
	s_mov_b32 s96, s0
	s_mov_b32 s97, s1
	s_cbranch_vccnz .Lepi0_p0
	s_lshl_b64 s[4:5], s[20:21], 11
	s_add_u32 s4, s64, s4
	s_addc_u32 s5, s65, s5
	v_lshlrev_b32_e32 v140, 1, v219
	v_lshl_add_u32 v140, v218, 13, v140
	v_mov_b32_e32 v141, 0
	v_lshl_add_u64 v[146:147], s[4:5], 0, v[140:141]
	s_mov_b64 s[100:101], 0x1000
	s_mov_b64 s[98:99], 0x4000
	global_load_dwordx4 v[166:169], v128, s[96:97]
	s_add_u32 s96, s96, 0x1000
	s_addc_u32 s97, s97, 0
	global_load_dwordx4 v[170:173], v128, s[96:97]
	s_add_u32 s96, s96, 0x1000
	s_addc_u32 s97, s97, 0
	global_load_dwordx4 v[174:177], v128, s[96:97]
	s_add_u32 s96, s96, 0x1000
	s_addc_u32 s97, s97, 0
	global_load_dwordx4 v[178:181], v128, s[96:97]
	s_add_u32 s96, s96, 0x1000
	s_addc_u32 s97, s97, 0
	global_load_dwordx4 v[182:185], v128, s[96:97]
	s_add_u32 s96, s96, 0x1000
	s_addc_u32 s97, s97, 0
	global_load_dwordx4 v[186:189], v128, s[96:97]
	s_add_u32 s96, s96, 0x1000
	s_addc_u32 s97, s97, 0
	global_load_dwordx4 v[190:193], v128, s[96:97]
	s_add_u32 s96, s96, 0x1000
	s_addc_u32 s97, s97, 0
	global_load_dwordx4 v[194:197], v128, s[96:97]
	s_add_u32 s96, s96, 0x1000
	s_addc_u32 s97, s97, 0
	global_load_dwordx4 v[198:201], v128, s[96:97]
	s_add_u32 s96, s96, 0x1000
	s_addc_u32 s97, s97, 0
	global_load_dwordx4 v[202:205], v128, s[96:97]
	s_add_u32 s96, s96, 0x1000
	s_addc_u32 s97, s97, 0
	global_load_dwordx4 v[240:243], v128, s[96:97]
	s_add_u32 s96, s96, 0x1000
	s_addc_u32 s97, s97, 0
	global_load_dwordx4 v[244:247], v128, s[96:97]
	s_add_u32 s96, s96, 0x1000
	s_addc_u32 s97, s97, 0
	global_load_dwordx4 v[248:251], v128, s[96:97]
	s_add_u32 s96, s96, 0x1000
	s_addc_u32 s97, s97, 0
	global_load_dwordx4 v[252:255], v128, s[96:97]
	s_add_u32 s96, s96, 0x1000
	s_addc_u32 s97, s97, 0
	global_load_dwordx4 v[232:235], v128, s[96:97]
	s_add_u32 s96, s96, 0x1000
	s_addc_u32 s97, s97, 0
	global_load_dwordx4 v[154:157], v128, s[96:97]
	s_add_u32 s96, s96, 0x1000
	s_addc_u32 s97, s97, 0
	s_waitcnt vmcnt(8)
	v_lshl_add_u64 v[148:149], v[146:147], 0, s[100:101]
	v_mul_f32_e32 v158, v0, v142
	v_fma_f32 v166, -v209, v158, v166
	v_bfe_u32 v158, v166, 16, 1
	v_add3_u32 v166, v166, v158, s39
	global_store_short_d16_hi v[146:147], v166, off
	v_mul_f32_e32 v159, v1, v145
	v_fma_f32 v167, -v209, v159, v167
	v_bfe_u32 v159, v167, 16, 1
	v_add3_u32 v167, v167, v159, s39
	global_store_short_d16_hi v[146:147], v167, off offset:2048
	v_mul_f32_e32 v160, v2, v152
	v_fma_f32 v168, -v209, v160, v168
	v_bfe_u32 v160, v168, 16, 1
	v_add3_u32 v168, v168, v160, s39
	global_store_short_d16_hi v[148:149], v168, off
	v_mul_f32_e32 v150, v3, v161
	v_fma_f32 v169, -v209, v150, v169
	v_bfe_u32 v150, v169, 16, 1
	v_add3_u32 v169, v169, v150, s39
	global_store_short_d16_hi v[148:149], v169, off offset:2048
	v_mul_f32_e32 v158, v112, v142
	v_fma_f32 v170, -v209, v158, v170
	v_bfe_u32 v158, v170, 16, 1
	v_add3_u32 v170, v170, v158, s39
	global_store_short_d16_hi v[146:147], v170, off offset:64
	v_mul_f32_e32 v159, v113, v145
	v_fma_f32 v171, -v209, v159, v171
	v_bfe_u32 v159, v171, 16, 1
	v_add3_u32 v171, v171, v159, s39
	global_store_short_d16_hi v[146:147], v171, off offset:2112
	v_mul_f32_e32 v160, v114, v152
	v_fma_f32 v172, -v209, v160, v172
	v_bfe_u32 v160, v172, 16, 1
	v_add3_u32 v172, v172, v160, s39
	global_store_short_d16_hi v[148:149], v172, off offset:64
	v_mul_f32_e32 v150, v115, v161
	v_fma_f32 v173, -v209, v150, v173
	v_bfe_u32 v150, v173, 16, 1
	v_add3_u32 v173, v173, v150, s39
	global_store_short_d16_hi v[148:149], v173, off offset:2112
	v_mul_f32_e32 v158, v96, v142
	v_fma_f32 v174, -v209, v158, v174
	v_bfe_u32 v158, v174, 16, 1
	v_add3_u32 v174, v174, v158, s39
	global_store_short_d16_hi v[146:147], v174, off offset:128
	v_mul_f32_e32 v159, v97, v145
	v_fma_f32 v175, -v209, v159, v175
	v_bfe_u32 v159, v175, 16, 1
	v_add3_u32 v175, v175, v159, s39
	global_store_short_d16_hi v[146:147], v175, off offset:2176
	v_mul_f32_e32 v160, v98, v152
	v_fma_f32 v176, -v209, v160, v176
	v_bfe_u32 v160, v176, 16, 1
	v_add3_u32 v176, v176, v160, s39
	global_store_short_d16_hi v[148:149], v176, off offset:128
	v_mul_f32_e32 v150, v99, v161
	v_fma_f32 v177, -v209, v150, v177
	v_bfe_u32 v150, v177, 16, 1
	v_add3_u32 v177, v177, v150, s39
	global_store_short_d16_hi v[148:149], v177, off offset:2176
	v_mul_f32_e32 v158, v80, v142
	v_fma_f32 v178, -v209, v158, v178
	v_bfe_u32 v158, v178, 16, 1
	v_add3_u32 v178, v178, v158, s39
	global_store_short_d16_hi v[146:147], v178, off offset:192
	v_mul_f32_e32 v159, v81, v145
	v_fma_f32 v179, -v209, v159, v179
	v_bfe_u32 v159, v179, 16, 1
	v_add3_u32 v179, v179, v159, s39
	global_store_short_d16_hi v[146:147], v179, off offset:2240
	v_mul_f32_e32 v160, v82, v152
	v_fma_f32 v180, -v209, v160, v180
	v_bfe_u32 v160, v180, 16, 1
	v_add3_u32 v180, v180, v160, s39
	global_store_short_d16_hi v[148:149], v180, off offset:192
	v_mul_f32_e32 v150, v83, v161
	v_fma_f32 v181, -v209, v150, v181
	v_bfe_u32 v150, v181, 16, 1
	v_add3_u32 v181, v181, v150, s39
	global_store_short_d16_hi v[148:149], v181, off offset:2240
	v_mul_f32_e32 v158, v64, v142
	v_fma_f32 v182, -v209, v158, v182
	v_bfe_u32 v158, v182, 16, 1
	v_add3_u32 v182, v182, v158, s39
	global_store_short_d16_hi v[146:147], v182, off offset:256
	v_mul_f32_e32 v159, v65, v145
	v_fma_f32 v183, -v209, v159, v183
	v_bfe_u32 v159, v183, 16, 1
	v_add3_u32 v183, v183, v159, s39
	global_store_short_d16_hi v[146:147], v183, off offset:2304
	v_mul_f32_e32 v160, v66, v152
	v_fma_f32 v184, -v209, v160, v184
	v_bfe_u32 v160, v184, 16, 1
	v_add3_u32 v184, v184, v160, s39
	global_store_short_d16_hi v[148:149], v184, off offset:256
	v_mul_f32_e32 v150, v67, v161
	v_fma_f32 v185, -v209, v150, v185
	v_bfe_u32 v150, v185, 16, 1
	v_add3_u32 v185, v185, v150, s39
	global_store_short_d16_hi v[148:149], v185, off offset:2304
	v_mul_f32_e32 v158, v48, v142
	v_fma_f32 v186, -v209, v158, v186
	v_bfe_u32 v158, v186, 16, 1
	v_add3_u32 v186, v186, v158, s39
	global_store_short_d16_hi v[146:147], v186, off offset:320
	v_mul_f32_e32 v159, v49, v145
	v_fma_f32 v187, -v209, v159, v187
	v_bfe_u32 v159, v187, 16, 1
	v_add3_u32 v187, v187, v159, s39
	global_store_short_d16_hi v[146:147], v187, off offset:2368
	v_mul_f32_e32 v160, v50, v152
	v_fma_f32 v188, -v209, v160, v188
	v_bfe_u32 v160, v188, 16, 1
	v_add3_u32 v188, v188, v160, s39
	global_store_short_d16_hi v[148:149], v188, off offset:320
	v_mul_f32_e32 v150, v51, v161
	v_fma_f32 v189, -v209, v150, v189
	v_bfe_u32 v150, v189, 16, 1
	v_add3_u32 v189, v189, v150, s39
	global_store_short_d16_hi v[148:149], v189, off offset:2368
	v_mul_f32_e32 v158, v32, v142
	v_fma_f32 v190, -v209, v158, v190
	v_bfe_u32 v158, v190, 16, 1
	v_add3_u32 v190, v190, v158, s39
	global_store_short_d16_hi v[146:147], v190, off offset:384
	v_mul_f32_e32 v159, v33, v145
	v_fma_f32 v191, -v209, v159, v191
	v_bfe_u32 v159, v191, 16, 1
	v_add3_u32 v191, v191, v159, s39
	global_store_short_d16_hi v[146:147], v191, off offset:2432
	v_mul_f32_e32 v160, v34, v152
	v_fma_f32 v192, -v209, v160, v192
	v_bfe_u32 v160, v192, 16, 1
	v_add3_u32 v192, v192, v160, s39
	global_store_short_d16_hi v[148:149], v192, off offset:384
	v_mul_f32_e32 v150, v35, v161
	v_fma_f32 v193, -v209, v150, v193
	v_bfe_u32 v150, v193, 16, 1
	v_add3_u32 v193, v193, v150, s39
	global_store_short_d16_hi v[148:149], v193, off offset:2432
	v_mul_f32_e32 v158, v16, v142
	v_fma_f32 v194, -v209, v158, v194
	v_bfe_u32 v158, v194, 16, 1
	v_add3_u32 v194, v194, v158, s39
	global_store_short_d16_hi v[146:147], v194, off offset:448
	v_mul_f32_e32 v159, v17, v145
	v_fma_f32 v195, -v209, v159, v195
	v_bfe_u32 v159, v195, 16, 1
	v_add3_u32 v195, v195, v159, s39
	global_store_short_d16_hi v[146:147], v195, off offset:2496
	v_mul_f32_e32 v160, v18, v152
	v_fma_f32 v196, -v209, v160, v196
	v_bfe_u32 v160, v196, 16, 1
	v_add3_u32 v196, v196, v160, s39
	global_store_short_d16_hi v[148:149], v196, off offset:448
	v_mul_f32_e32 v150, v19, v161
	v_fma_f32 v197, -v209, v150, v197
	v_bfe_u32 v150, v197, 16, 1
	v_add3_u32 v197, v197, v150, s39
	global_store_short_d16_hi v[148:149], v197, off offset:2496
	global_load_dwordx4 v[166:169], v128, s[96:97]
	s_add_u32 s96, s96, 0x1000
	s_addc_u32 s97, s97, 0
	global_load_dwordx4 v[170:173], v128, s[96:97]
	s_add_u32 s96, s96, 0x1000
	s_addc_u32 s97, s97, 0
	global_load_dwordx4 v[174:177], v128, s[96:97]
	s_add_u32 s96, s96, 0x1000
	s_addc_u32 s97, s97, 0
	global_load_dwordx4 v[178:181], v128, s[96:97]
	s_add_u32 s96, s96, 0x1000
	s_addc_u32 s97, s97, 0
	global_load_dwordx4 v[182:185], v128, s[96:97]
	s_add_u32 s96, s96, 0x1000
	s_addc_u32 s97, s97, 0
	global_load_dwordx4 v[186:189], v128, s[96:97]
	s_add_u32 s96, s96, 0x1000
	s_addc_u32 s97, s97, 0
	global_load_dwordx4 v[190:193], v128, s[96:97]
	s_add_u32 s96, s96, 0x1000
	s_addc_u32 s97, s97, 0
	global_load_dwordx4 v[194:197], v128, s[96:97]
	s_add_u32 s96, s96, 0x1000
	s_addc_u32 s97, s97, 0
	v_lshl_add_u64 v[146:147], v[146:147], 0, s[98:99]
	s_waitcnt vmcnt(40)
	v_lshl_add_u64 v[148:149], v[146:147], 0, s[100:101]
	v_mul_f32_e32 v158, v4, v162
	v_fma_f32 v198, -v209, v158, v198
	v_bfe_u32 v158, v198, 16, 1
	v_add3_u32 v198, v198, v158, s39
	global_store_short_d16_hi v[146:147], v198, off
	v_mul_f32_e32 v159, v5, v163
	v_fma_f32 v199, -v209, v159, v199
	v_bfe_u32 v159, v199, 16, 1
	v_add3_u32 v199, v199, v159, s39
	global_store_short_d16_hi v[146:147], v199, off offset:2048
	v_mul_f32_e32 v160, v6, v164
	v_fma_f32 v200, -v209, v160, v200
	v_bfe_u32 v160, v200, 16, 1
	v_add3_u32 v200, v200, v160, s39
	global_store_short_d16_hi v[148:149], v200, off
	v_mul_f32_e32 v150, v7, v165
	v_fma_f32 v201, -v209, v150, v201
	v_bfe_u32 v150, v201, 16, 1
	v_add3_u32 v201, v201, v150, s39
	global_store_short_d16_hi v[148:149], v201, off offset:2048
	v_mul_f32_e32 v158, v116, v162
	v_fma_f32 v202, -v209, v158, v202
	v_bfe_u32 v158, v202, 16, 1
	v_add3_u32 v202, v202, v158, s39
	global_store_short_d16_hi v[146:147], v202, off offset:64
	v_mul_f32_e32 v159, v117, v163
	v_fma_f32 v203, -v209, v159, v203
	v_bfe_u32 v159, v203, 16, 1
	v_add3_u32 v203, v203, v159, s39
	global_store_short_d16_hi v[146:147], v203, off offset:2112
	v_mul_f32_e32 v160, v118, v164
	v_fma_f32 v204, -v209, v160, v204
	v_bfe_u32 v160, v204, 16, 1
	v_add3_u32 v204, v204, v160, s39
	global_store_short_d16_hi v[148:149], v204, off offset:64
	v_mul_f32_e32 v150, v119, v165
	v_fma_f32 v205, -v209, v150, v205
	v_bfe_u32 v150, v205, 16, 1
	v_add3_u32 v205, v205, v150, s39
	global_store_short_d16_hi v[148:149], v205, off offset:2112
	v_mul_f32_e32 v158, v100, v162
	v_fma_f32 v240, -v209, v158, v240
	v_bfe_u32 v158, v240, 16, 1
	v_add3_u32 v240, v240, v158, s39
	global_store_short_d16_hi v[146:147], v240, off offset:128
	v_mul_f32_e32 v159, v101, v163
	v_fma_f32 v241, -v209, v159, v241
	v_bfe_u32 v159, v241, 16, 1
	v_add3_u32 v241, v241, v159, s39
	global_store_short_d16_hi v[146:147], v241, off offset:2176
	v_mul_f32_e32 v160, v102, v164
	v_fma_f32 v242, -v209, v160, v242
	v_bfe_u32 v160, v242, 16, 1
	v_add3_u32 v242, v242, v160, s39
	global_store_short_d16_hi v[148:149], v242, off offset:128
	v_mul_f32_e32 v150, v103, v165
	v_fma_f32 v243, -v209, v150, v243
	v_bfe_u32 v150, v243, 16, 1
	v_add3_u32 v243, v243, v150, s39
	global_store_short_d16_hi v[148:149], v243, off offset:2176
	v_mul_f32_e32 v158, v84, v162
	v_fma_f32 v244, -v209, v158, v244
	v_bfe_u32 v158, v244, 16, 1
	v_add3_u32 v244, v244, v158, s39
	global_store_short_d16_hi v[146:147], v244, off offset:192
	v_mul_f32_e32 v159, v85, v163
	v_fma_f32 v245, -v209, v159, v245
	v_bfe_u32 v159, v245, 16, 1
	v_add3_u32 v245, v245, v159, s39
	global_store_short_d16_hi v[146:147], v245, off offset:2240
	v_mul_f32_e32 v160, v86, v164
	v_fma_f32 v246, -v209, v160, v246
	v_bfe_u32 v160, v246, 16, 1
	v_add3_u32 v246, v246, v160, s39
	global_store_short_d16_hi v[148:149], v246, off offset:192
	v_mul_f32_e32 v150, v87, v165
	v_fma_f32 v247, -v209, v150, v247
	v_bfe_u32 v150, v247, 16, 1
	v_add3_u32 v247, v247, v150, s39
	global_store_short_d16_hi v[148:149], v247, off offset:2240
	v_mul_f32_e32 v158, v68, v162
	v_fma_f32 v248, -v209, v158, v248
	v_bfe_u32 v158, v248, 16, 1
	v_add3_u32 v248, v248, v158, s39
	global_store_short_d16_hi v[146:147], v248, off offset:256
	v_mul_f32_e32 v159, v69, v163
	v_fma_f32 v249, -v209, v159, v249
	v_bfe_u32 v159, v249, 16, 1
	v_add3_u32 v249, v249, v159, s39
	global_store_short_d16_hi v[146:147], v249, off offset:2304
	v_mul_f32_e32 v160, v70, v164
	v_fma_f32 v250, -v209, v160, v250
	v_bfe_u32 v160, v250, 16, 1
	v_add3_u32 v250, v250, v160, s39
	global_store_short_d16_hi v[148:149], v250, off offset:256
	v_mul_f32_e32 v150, v71, v165
	v_fma_f32 v251, -v209, v150, v251
	v_bfe_u32 v150, v251, 16, 1
	v_add3_u32 v251, v251, v150, s39
	global_store_short_d16_hi v[148:149], v251, off offset:2304
	v_mul_f32_e32 v158, v52, v162
	v_fma_f32 v252, -v209, v158, v252
	v_bfe_u32 v158, v252, 16, 1
	v_add3_u32 v252, v252, v158, s39
	global_store_short_d16_hi v[146:147], v252, off offset:320
	v_mul_f32_e32 v159, v53, v163
	v_fma_f32 v253, -v209, v159, v253
	v_bfe_u32 v159, v253, 16, 1
	v_add3_u32 v253, v253, v159, s39
	global_store_short_d16_hi v[146:147], v253, off offset:2368
	v_mul_f32_e32 v160, v54, v164
	v_fma_f32 v254, -v209, v160, v254
	v_bfe_u32 v160, v254, 16, 1
	v_add3_u32 v254, v254, v160, s39
	global_store_short_d16_hi v[148:149], v254, off offset:320
	v_mul_f32_e32 v150, v55, v165
	v_fma_f32 v255, -v209, v150, v255
	v_bfe_u32 v150, v255, 16, 1
	v_add3_u32 v255, v255, v150, s39
	global_store_short_d16_hi v[148:149], v255, off offset:2368
	v_mul_f32_e32 v158, v36, v162
	v_fma_f32 v232, -v209, v158, v232
	v_bfe_u32 v158, v232, 16, 1
	v_add3_u32 v232, v232, v158, s39
	global_store_short_d16_hi v[146:147], v232, off offset:384
	v_mul_f32_e32 v159, v37, v163
	v_fma_f32 v233, -v209, v159, v233
	v_bfe_u32 v159, v233, 16, 1
	v_add3_u32 v233, v233, v159, s39
	global_store_short_d16_hi v[146:147], v233, off offset:2432
	v_mul_f32_e32 v160, v38, v164
	v_fma_f32 v234, -v209, v160, v234
	v_bfe_u32 v160, v234, 16, 1
	v_add3_u32 v234, v234, v160, s39
	global_store_short_d16_hi v[148:149], v234, off offset:384
	v_mul_f32_e32 v150, v39, v165
	v_fma_f32 v235, -v209, v150, v235
	v_bfe_u32 v150, v235, 16, 1
	v_add3_u32 v235, v235, v150, s39
	global_store_short_d16_hi v[148:149], v235, off offset:2432
	v_mul_f32_e32 v158, v20, v162
	v_fma_f32 v154, -v209, v158, v154
	v_bfe_u32 v158, v154, 16, 1
	v_add3_u32 v154, v154, v158, s39
	global_store_short_d16_hi v[146:147], v154, off offset:448
	v_mul_f32_e32 v159, v21, v163
	v_fma_f32 v155, -v209, v159, v155
	v_bfe_u32 v159, v155, 16, 1
	v_add3_u32 v155, v155, v159, s39
	global_store_short_d16_hi v[146:147], v155, off offset:2496
	v_mul_f32_e32 v160, v22, v164
	v_fma_f32 v156, -v209, v160, v156
	v_bfe_u32 v160, v156, 16, 1
	v_add3_u32 v156, v156, v160, s39
	global_store_short_d16_hi v[148:149], v156, off offset:448
	v_mul_f32_e32 v150, v23, v165
	v_fma_f32 v157, -v209, v150, v157
	v_bfe_u32 v150, v157, 16, 1
	v_add3_u32 v157, v157, v150, s39
	global_store_short_d16_hi v[148:149], v157, off offset:2496
	global_load_dwordx4 v[198:201], v128, s[96:97]
	s_add_u32 s96, s96, 0x1000
	s_addc_u32 s97, s97, 0
	global_load_dwordx4 v[202:205], v128, s[96:97]
	s_add_u32 s96, s96, 0x1000
	s_addc_u32 s97, s97, 0
	global_load_dwordx4 v[240:243], v128, s[96:97]
	s_add_u32 s96, s96, 0x1000
	s_addc_u32 s97, s97, 0
	global_load_dwordx4 v[244:247], v128, s[96:97]
	s_add_u32 s96, s96, 0x1000
	s_addc_u32 s97, s97, 0
	global_load_dwordx4 v[248:251], v128, s[96:97]
	s_add_u32 s96, s96, 0x1000
	s_addc_u32 s97, s97, 0
	global_load_dwordx4 v[252:255], v128, s[96:97]
	s_add_u32 s96, s96, 0x1000
	s_addc_u32 s97, s97, 0
	global_load_dwordx4 v[232:235], v128, s[96:97]
	s_add_u32 s96, s96, 0x1000
	s_addc_u32 s97, s97, 0
	global_load_dwordx4 v[154:157], v128, s[96:97]
	s_add_u32 s96, s96, 0x1000
	s_addc_u32 s97, s97, 0
	v_lshl_add_u64 v[146:147], v[146:147], 0, s[98:99]
	s_waitcnt vmcnt(40)
	v_lshl_add_u64 v[148:149], v[146:147], 0, s[100:101]
	v_mul_f32_e32 v158, v8, v137
	v_fma_f32 v166, -v209, v158, v166
	v_bfe_u32 v158, v166, 16, 1
	v_add3_u32 v166, v166, v158, s39
	global_store_short_d16_hi v[146:147], v166, off
	v_mul_f32_e32 v159, v9, v136
	v_fma_f32 v167, -v209, v159, v167
	v_bfe_u32 v159, v167, 16, 1
	v_add3_u32 v167, v167, v159, s39
	global_store_short_d16_hi v[146:147], v167, off offset:2048
	v_mul_f32_e32 v160, v10, v135
	v_fma_f32 v168, -v209, v160, v168
	v_bfe_u32 v160, v168, 16, 1
	v_add3_u32 v168, v168, v160, s39
	global_store_short_d16_hi v[148:149], v168, off
	v_mul_f32_e32 v150, v11, v134
	v_fma_f32 v169, -v209, v150, v169
	v_bfe_u32 v150, v169, 16, 1
	v_add3_u32 v169, v169, v150, s39
	global_store_short_d16_hi v[148:149], v169, off offset:2048
	v_mul_f32_e32 v158, v120, v137
	v_fma_f32 v170, -v209, v158, v170
	v_bfe_u32 v158, v170, 16, 1
	v_add3_u32 v170, v170, v158, s39
	global_store_short_d16_hi v[146:147], v170, off offset:64
	v_mul_f32_e32 v159, v121, v136
	v_fma_f32 v171, -v209, v159, v171
	v_bfe_u32 v159, v171, 16, 1
	v_add3_u32 v171, v171, v159, s39
	global_store_short_d16_hi v[146:147], v171, off offset:2112
	v_mul_f32_e32 v160, v122, v135
	v_fma_f32 v172, -v209, v160, v172
	v_bfe_u32 v160, v172, 16, 1
	v_add3_u32 v172, v172, v160, s39
	global_store_short_d16_hi v[148:149], v172, off offset:64
	v_mul_f32_e32 v150, v123, v134
	v_fma_f32 v173, -v209, v150, v173
	v_bfe_u32 v150, v173, 16, 1
	v_add3_u32 v173, v173, v150, s39
	global_store_short_d16_hi v[148:149], v173, off offset:2112
	v_mul_f32_e32 v158, v104, v137
	v_fma_f32 v174, -v209, v158, v174
	v_bfe_u32 v158, v174, 16, 1
	v_add3_u32 v174, v174, v158, s39
	global_store_short_d16_hi v[146:147], v174, off offset:128
	v_mul_f32_e32 v159, v105, v136
	v_fma_f32 v175, -v209, v159, v175
	v_bfe_u32 v159, v175, 16, 1
	v_add3_u32 v175, v175, v159, s39
	global_store_short_d16_hi v[146:147], v175, off offset:2176
	v_mul_f32_e32 v160, v106, v135
	v_fma_f32 v176, -v209, v160, v176
	v_bfe_u32 v160, v176, 16, 1
	v_add3_u32 v176, v176, v160, s39
	global_store_short_d16_hi v[148:149], v176, off offset:128
	v_mul_f32_e32 v150, v107, v134
	v_fma_f32 v177, -v209, v150, v177
	v_bfe_u32 v150, v177, 16, 1
	v_add3_u32 v177, v177, v150, s39
	global_store_short_d16_hi v[148:149], v177, off offset:2176
	v_mul_f32_e32 v158, v88, v137
	v_fma_f32 v178, -v209, v158, v178
	v_bfe_u32 v158, v178, 16, 1
	v_add3_u32 v178, v178, v158, s39
	global_store_short_d16_hi v[146:147], v178, off offset:192
	v_mul_f32_e32 v159, v89, v136
	v_fma_f32 v179, -v209, v159, v179
	v_bfe_u32 v159, v179, 16, 1
	v_add3_u32 v179, v179, v159, s39
	global_store_short_d16_hi v[146:147], v179, off offset:2240
	v_mul_f32_e32 v160, v90, v135
	v_fma_f32 v180, -v209, v160, v180
	v_bfe_u32 v160, v180, 16, 1
	v_add3_u32 v180, v180, v160, s39
	global_store_short_d16_hi v[148:149], v180, off offset:192
	v_mul_f32_e32 v150, v91, v134
	v_fma_f32 v181, -v209, v150, v181
	v_bfe_u32 v150, v181, 16, 1
	v_add3_u32 v181, v181, v150, s39
	global_store_short_d16_hi v[148:149], v181, off offset:2240
	v_mul_f32_e32 v158, v72, v137
	v_fma_f32 v182, -v209, v158, v182
	v_bfe_u32 v158, v182, 16, 1
	v_add3_u32 v182, v182, v158, s39
	global_store_short_d16_hi v[146:147], v182, off offset:256
	v_mul_f32_e32 v159, v73, v136
	v_fma_f32 v183, -v209, v159, v183
	v_bfe_u32 v159, v183, 16, 1
	v_add3_u32 v183, v183, v159, s39
	global_store_short_d16_hi v[146:147], v183, off offset:2304
	v_mul_f32_e32 v160, v74, v135
	v_fma_f32 v184, -v209, v160, v184
	v_bfe_u32 v160, v184, 16, 1
	v_add3_u32 v184, v184, v160, s39
	global_store_short_d16_hi v[148:149], v184, off offset:256
	v_mul_f32_e32 v150, v75, v134
	v_fma_f32 v185, -v209, v150, v185
	v_bfe_u32 v150, v185, 16, 1
	v_add3_u32 v185, v185, v150, s39
	global_store_short_d16_hi v[148:149], v185, off offset:2304
	v_mul_f32_e32 v158, v56, v137
	v_fma_f32 v186, -v209, v158, v186
	v_bfe_u32 v158, v186, 16, 1
	v_add3_u32 v186, v186, v158, s39
	global_store_short_d16_hi v[146:147], v186, off offset:320
	v_mul_f32_e32 v159, v57, v136
	v_fma_f32 v187, -v209, v159, v187
	v_bfe_u32 v159, v187, 16, 1
	v_add3_u32 v187, v187, v159, s39
	global_store_short_d16_hi v[146:147], v187, off offset:2368
	v_mul_f32_e32 v160, v58, v135
	v_fma_f32 v188, -v209, v160, v188
	v_bfe_u32 v160, v188, 16, 1
	v_add3_u32 v188, v188, v160, s39
	global_store_short_d16_hi v[148:149], v188, off offset:320
	v_mul_f32_e32 v150, v59, v134
	v_fma_f32 v189, -v209, v150, v189
	v_bfe_u32 v150, v189, 16, 1
	v_add3_u32 v189, v189, v150, s39
	global_store_short_d16_hi v[148:149], v189, off offset:2368
	v_mul_f32_e32 v158, v40, v137
	v_fma_f32 v190, -v209, v158, v190
	v_bfe_u32 v158, v190, 16, 1
	v_add3_u32 v190, v190, v158, s39
	global_store_short_d16_hi v[146:147], v190, off offset:384
	v_mul_f32_e32 v159, v41, v136
	v_fma_f32 v191, -v209, v159, v191
	v_bfe_u32 v159, v191, 16, 1
	v_add3_u32 v191, v191, v159, s39
	global_store_short_d16_hi v[146:147], v191, off offset:2432
	v_mul_f32_e32 v160, v42, v135
	v_fma_f32 v192, -v209, v160, v192
	v_bfe_u32 v160, v192, 16, 1
	v_add3_u32 v192, v192, v160, s39
	global_store_short_d16_hi v[148:149], v192, off offset:384
	v_mul_f32_e32 v150, v43, v134
	v_fma_f32 v193, -v209, v150, v193
	v_bfe_u32 v150, v193, 16, 1
	v_add3_u32 v193, v193, v150, s39
	global_store_short_d16_hi v[148:149], v193, off offset:2432
	v_mul_f32_e32 v158, v24, v137
	v_fma_f32 v194, -v209, v158, v194
	v_bfe_u32 v158, v194, 16, 1
	v_add3_u32 v194, v194, v158, s39
	global_store_short_d16_hi v[146:147], v194, off offset:448
	v_mul_f32_e32 v159, v25, v136
	v_fma_f32 v195, -v209, v159, v195
	v_bfe_u32 v159, v195, 16, 1
	v_add3_u32 v195, v195, v159, s39
	global_store_short_d16_hi v[146:147], v195, off offset:2496
	v_mul_f32_e32 v160, v26, v135
	v_fma_f32 v196, -v209, v160, v196
	v_bfe_u32 v160, v196, 16, 1
	v_add3_u32 v196, v196, v160, s39
	global_store_short_d16_hi v[148:149], v196, off offset:448
	v_mul_f32_e32 v150, v27, v134
	v_fma_f32 v197, -v209, v150, v197
	v_bfe_u32 v150, v197, 16, 1
	v_add3_u32 v197, v197, v150, s39
	global_store_short_d16_hi v[148:149], v197, off offset:2496
	v_lshl_add_u64 v[146:147], v[146:147], 0, s[98:99]
	s_waitcnt vmcnt(32)
	v_lshl_add_u64 v[148:149], v[146:147], 0, s[100:101]
	v_mul_f32_e32 v158, v12, v133
	v_fma_f32 v198, -v209, v158, v198
	v_bfe_u32 v158, v198, 16, 1
	v_add3_u32 v198, v198, v158, s39
	global_store_short_d16_hi v[146:147], v198, off
	v_mul_f32_e32 v159, v13, v132
	v_fma_f32 v199, -v209, v159, v199
	v_bfe_u32 v159, v199, 16, 1
	v_add3_u32 v199, v199, v159, s39
	global_store_short_d16_hi v[146:147], v199, off offset:2048
	v_mul_f32_e32 v160, v14, v131
	v_fma_f32 v200, -v209, v160, v200
	v_bfe_u32 v160, v200, 16, 1
	v_add3_u32 v200, v200, v160, s39
	global_store_short_d16_hi v[148:149], v200, off
	v_mul_f32_e32 v150, v15, v130
	v_fma_f32 v201, -v209, v150, v201
	v_bfe_u32 v150, v201, 16, 1
	v_add3_u32 v201, v201, v150, s39
	global_store_short_d16_hi v[148:149], v201, off offset:2048
	v_mul_f32_e32 v158, v124, v133
	v_fma_f32 v202, -v209, v158, v202
	v_bfe_u32 v158, v202, 16, 1
	v_add3_u32 v202, v202, v158, s39
	global_store_short_d16_hi v[146:147], v202, off offset:64
	v_mul_f32_e32 v159, v125, v132
	v_fma_f32 v203, -v209, v159, v203
	v_bfe_u32 v159, v203, 16, 1
	v_add3_u32 v203, v203, v159, s39
	global_store_short_d16_hi v[146:147], v203, off offset:2112
	v_mul_f32_e32 v160, v126, v131
	v_fma_f32 v204, -v209, v160, v204
	v_bfe_u32 v160, v204, 16, 1
	v_add3_u32 v204, v204, v160, s39
	global_store_short_d16_hi v[148:149], v204, off offset:64
	v_mul_f32_e32 v150, v127, v130
	v_fma_f32 v205, -v209, v150, v205
	v_bfe_u32 v150, v205, 16, 1
	v_add3_u32 v205, v205, v150, s39
	global_store_short_d16_hi v[148:149], v205, off offset:2112
	v_mul_f32_e32 v158, v108, v133
	v_fma_f32 v240, -v209, v158, v240
	v_bfe_u32 v158, v240, 16, 1
	v_add3_u32 v240, v240, v158, s39
	global_store_short_d16_hi v[146:147], v240, off offset:128
	v_mul_f32_e32 v159, v109, v132
	v_fma_f32 v241, -v209, v159, v241
	v_bfe_u32 v159, v241, 16, 1
	v_add3_u32 v241, v241, v159, s39
	global_store_short_d16_hi v[146:147], v241, off offset:2176
	v_mul_f32_e32 v160, v110, v131
	v_fma_f32 v242, -v209, v160, v242
	v_bfe_u32 v160, v242, 16, 1
	v_add3_u32 v242, v242, v160, s39
	global_store_short_d16_hi v[148:149], v242, off offset:128
	v_mul_f32_e32 v150, v111, v130
	v_fma_f32 v243, -v209, v150, v243
	v_bfe_u32 v150, v243, 16, 1
	v_add3_u32 v243, v243, v150, s39
	global_store_short_d16_hi v[148:149], v243, off offset:2176
	v_mul_f32_e32 v158, v92, v133
	v_fma_f32 v244, -v209, v158, v244
	v_bfe_u32 v158, v244, 16, 1
	v_add3_u32 v244, v244, v158, s39
	global_store_short_d16_hi v[146:147], v244, off offset:192
	v_mul_f32_e32 v159, v93, v132
	v_fma_f32 v245, -v209, v159, v245
	v_bfe_u32 v159, v245, 16, 1
	v_add3_u32 v245, v245, v159, s39
	global_store_short_d16_hi v[146:147], v245, off offset:2240
	v_mul_f32_e32 v160, v94, v131
	v_fma_f32 v246, -v209, v160, v246
	v_bfe_u32 v160, v246, 16, 1
	v_add3_u32 v246, v246, v160, s39
	global_store_short_d16_hi v[148:149], v246, off offset:192
	v_mul_f32_e32 v150, v95, v130
	v_fma_f32 v247, -v209, v150, v247
	v_bfe_u32 v150, v247, 16, 1
	v_add3_u32 v247, v247, v150, s39
	global_store_short_d16_hi v[148:149], v247, off offset:2240
	v_mul_f32_e32 v158, v76, v133
	v_fma_f32 v248, -v209, v158, v248
	v_bfe_u32 v158, v248, 16, 1
	v_add3_u32 v248, v248, v158, s39
	global_store_short_d16_hi v[146:147], v248, off offset:256
	v_mul_f32_e32 v159, v77, v132
	v_fma_f32 v249, -v209, v159, v249
	v_bfe_u32 v159, v249, 16, 1
	v_add3_u32 v249, v249, v159, s39
	global_store_short_d16_hi v[146:147], v249, off offset:2304
	v_mul_f32_e32 v160, v78, v131
	v_fma_f32 v250, -v209, v160, v250
	v_bfe_u32 v160, v250, 16, 1
	v_add3_u32 v250, v250, v160, s39
	global_store_short_d16_hi v[148:149], v250, off offset:256
	v_mul_f32_e32 v150, v79, v130
	v_fma_f32 v251, -v209, v150, v251
	v_bfe_u32 v150, v251, 16, 1
	v_add3_u32 v251, v251, v150, s39
	global_store_short_d16_hi v[148:149], v251, off offset:2304
	v_mul_f32_e32 v158, v60, v133
	v_fma_f32 v252, -v209, v158, v252
	v_bfe_u32 v158, v252, 16, 1
	v_add3_u32 v252, v252, v158, s39
	global_store_short_d16_hi v[146:147], v252, off offset:320
	v_mul_f32_e32 v159, v61, v132
	v_fma_f32 v253, -v209, v159, v253
	v_bfe_u32 v159, v253, 16, 1
	v_add3_u32 v253, v253, v159, s39
	global_store_short_d16_hi v[146:147], v253, off offset:2368
	v_mul_f32_e32 v160, v62, v131
	v_fma_f32 v254, -v209, v160, v254
	v_bfe_u32 v160, v254, 16, 1
	v_add3_u32 v254, v254, v160, s39
	global_store_short_d16_hi v[148:149], v254, off offset:320
	v_mul_f32_e32 v150, v63, v130
	v_fma_f32 v255, -v209, v150, v255
	v_bfe_u32 v150, v255, 16, 1
	v_add3_u32 v255, v255, v150, s39
	global_store_short_d16_hi v[148:149], v255, off offset:2368
	v_mul_f32_e32 v158, v44, v133
	v_fma_f32 v232, -v209, v158, v232
	v_bfe_u32 v158, v232, 16, 1
	v_add3_u32 v232, v232, v158, s39
	global_store_short_d16_hi v[146:147], v232, off offset:384
	v_mul_f32_e32 v159, v45, v132
	v_fma_f32 v233, -v209, v159, v233
	v_bfe_u32 v159, v233, 16, 1
	v_add3_u32 v233, v233, v159, s39
	global_store_short_d16_hi v[146:147], v233, off offset:2432
	v_mul_f32_e32 v160, v46, v131
	v_fma_f32 v234, -v209, v160, v234
	v_bfe_u32 v160, v234, 16, 1
	v_add3_u32 v234, v234, v160, s39
	global_store_short_d16_hi v[148:149], v234, off offset:384
	v_mul_f32_e32 v150, v47, v130
	v_fma_f32 v235, -v209, v150, v235
	v_bfe_u32 v150, v235, 16, 1
	v_add3_u32 v235, v235, v150, s39
	global_store_short_d16_hi v[148:149], v235, off offset:2432
	v_mul_f32_e32 v158, v28, v133
	v_fma_f32 v154, -v209, v158, v154
	v_bfe_u32 v158, v154, 16, 1
	v_add3_u32 v154, v154, v158, s39
	global_store_short_d16_hi v[146:147], v154, off offset:448
	v_mul_f32_e32 v159, v29, v132
	v_fma_f32 v155, -v209, v159, v155
	v_bfe_u32 v159, v155, 16, 1
	v_add3_u32 v155, v155, v159, s39
	global_store_short_d16_hi v[146:147], v155, off offset:2496
	v_mul_f32_e32 v160, v30, v131
	v_fma_f32 v156, -v209, v160, v156
	v_bfe_u32 v160, v156, 16, 1
	v_add3_u32 v156, v156, v160, s39
	global_store_short_d16_hi v[148:149], v156, off offset:448
	v_mul_f32_e32 v150, v31, v130
	v_fma_f32 v157, -v209, v150, v157
	v_bfe_u32 v150, v157, 16, 1
	v_add3_u32 v157, v157, v150, s39
	global_store_short_d16_hi v[148:149], v157, off offset:2496
	s_branch .LBB0_508

.LBB0_906:
	s_lshl_b32 s4, s80, 14
	v_add3_u32 v236, s4, v221, v220
	ds_read_b128 v[192:195], v236
	ds_read_b128 v[196:199], v236 offset:8192
	v_add3_u32 v236, s4, v222, v220
	ds_read_b128 v[200:203], v236
	ds_read_b128 v[204:207], v236 offset:8192
	v_add3_u32 v236, s4, v223, v220
	ds_read_b128 v[240:243], v236
	ds_read_b128 v[244:247], v236 offset:8192
	v_add3_u32 v236, s4, v225, v220
	ds_read_b128 v[248:251], v236
	ds_read_b128 v[252:255], v236 offset:8192
	s_waitcnt lgkmcnt(7)
	v_mfma_f32_32x32x16_bf16 v[144:159], v[192:195], v[160:163], 0
	s_waitcnt lgkmcnt(6)
	v_mfma_f32_32x32x16_bf16 v[128:143], v[196:199], v[160:163], 0
	v_add3_u32 v236, s4, v226, v220
	ds_read_b128 v[192:195], v236
	ds_read_b128 v[196:199], v236 offset:8192
	s_waitcnt lgkmcnt(7)
	v_mfma_f32_32x32x16_bf16 v[144:159], v[200:203], v[164:167], v[144:159]
	s_waitcnt lgkmcnt(6)
	v_mfma_f32_32x32x16_bf16 v[128:143], v[204:207], v[164:167], v[128:143]
	v_add3_u32 v236, s4, v227, v220
	ds_read_b128 v[200:203], v236
	ds_read_b128 v[204:207], v236 offset:8192
	s_waitcnt lgkmcnt(7)
	v_mfma_f32_32x32x16_bf16 v[144:159], v[240:243], v[168:171], v[144:159]
	s_waitcnt lgkmcnt(6)
	v_mfma_f32_32x32x16_bf16 v[128:143], v[244:247], v[168:171], v[128:143]
	v_add3_u32 v236, s4, v228, v220
	ds_read_b128 v[240:243], v236
	ds_read_b128 v[244:247], v236 offset:8192
	s_waitcnt lgkmcnt(7)
	v_mfma_f32_32x32x16_bf16 v[144:159], v[248:251], v[172:175], v[144:159]
	s_waitcnt lgkmcnt(6)
	v_mfma_f32_32x32x16_bf16 v[128:143], v[252:255], v[172:175], v[128:143]
	v_add3_u32 v236, s4, v229, v220
	ds_read_b128 v[248:251], v236
	ds_read_b128 v[252:255], v236 offset:8192
	s_waitcnt lgkmcnt(7)
	v_mfma_f32_32x32x16_bf16 v[144:159], v[192:195], v[176:179], v[144:159]
	s_waitcnt lgkmcnt(6)
	v_mfma_f32_32x32x16_bf16 v[128:143], v[196:199], v[176:179], v[128:143]
	s_waitcnt lgkmcnt(5)
	v_mfma_f32_32x32x16_bf16 v[144:159], v[200:203], v[180:183], v[144:159]
	s_waitcnt lgkmcnt(4)
	v_mfma_f32_32x32x16_bf16 v[128:143], v[204:207], v[180:183], v[128:143]
	s_waitcnt lgkmcnt(3)
	v_mfma_f32_32x32x16_bf16 v[144:159], v[240:243], v[184:187], v[144:159]
	s_waitcnt lgkmcnt(2)
	v_mfma_f32_32x32x16_bf16 v[128:143], v[244:247], v[184:187], v[128:143]
	s_waitcnt lgkmcnt(1)
	v_mfma_f32_32x32x16_bf16 v[144:159], v[248:251], v[188:191], v[144:159]
	s_waitcnt lgkmcnt(0)
	v_mfma_f32_32x32x16_bf16 v[128:143], v[252:255], v[188:191], v[128:143]
	s_nop 9
	v_max_f32_e32 v192, v144, v145
	v_max3_f32 v192, v192, v146, v147
	v_max3_f32 v192, v192, v148, v149
	v_max3_f32 v192, v192, v150, v151
	v_max3_f32 v192, v192, v152, v153
	v_max3_f32 v192, v192, v154, v155
	v_max3_f32 v192, v192, v156, v157
	v_max3_f32 v192, v192, v158, v159
	v_max3_f32 v192, v192, v128, v129
	v_max3_f32 v192, v192, v130, v131
	v_max3_f32 v192, v192, v132, v133
	v_max3_f32 v192, v192, v134, v135
	v_max3_f32 v192, v192, v136, v137
	v_max3_f32 v192, v192, v138, v139
	v_max3_f32 v192, v192, v140, v141
	v_max3_f32 v192, v192, v142, v143
	v_mov_b32_e32 v193, v192
	s_nop 1
	v_permlane32_swap_b32_e32 v192, v193
	v_max_f32_e32 v192, v192, v193
	v_sub_f32_e32 v193, v192, v231
	v_cmp_ge_f32_e32 vcc, s42, v193
	s_cmp_eq_u64 vcc, exec
	s_cbranch_scc1 .LBB0_910
	v_max_f32_e32 v234, v231, v192
	v_sub_f32_e32 v192, v231, v234
	v_mul_f32_e32 v192, 0x3e0293ee, v192
	v_exp_f32_e32 v233, v192
	v_mov_b32_e32 v231, v234
	v_mul_f32_e32 v237, 0xbe0293ee, v234
	v_mul_f32_e32 v232, v232, v233
	s_and_saveexec_b64 s[24:25], s[0:1]
	ds_write_b32 v224, v233 offset:128
	s_or_b64 exec, exec, s[24:25]
	s_waitcnt lgkmcnt(0)
	v_add_u32_e32 v192, s21, v210
	ds_read_b128 v[204:207], v192 offset:224
	ds_read_b128 v[200:203], v192 offset:192
	ds_read_b128 v[196:199], v192 offset:160
	ds_read_b128 v[192:195], v192 offset:128
	s_waitcnt lgkmcnt(3)
	v_pk_mul_f32 v[12:13], v[12:13], v[204:205]
	s_waitcnt lgkmcnt(2)
	v_pk_mul_f32 v[8:9], v[8:9], v[200:201]
	s_waitcnt lgkmcnt(1)
	v_pk_mul_f32 v[4:5], v[4:5], v[196:197]
	v_pk_mul_f32 v[14:15], v[14:15], v[206:207]
	v_pk_mul_f32 v[10:11], v[10:11], v[202:203]
	v_pk_mul_f32 v[6:7], v[6:7], v[198:199]
	s_waitcnt lgkmcnt(0)
	v_pk_mul_f32 v[2:3], v[2:3], v[194:195]
	v_pk_mul_f32 v[0:1], v[0:1], v[192:193]
	v_pk_mul_f32 v[124:125], v[124:125], v[204:205]
	v_pk_mul_f32 v[120:121], v[120:121], v[200:201]
	v_pk_mul_f32 v[116:117], v[116:117], v[196:197]
	v_pk_mul_f32 v[126:127], v[126:127], v[206:207]
	v_pk_mul_f32 v[122:123], v[122:123], v[202:203]
	v_pk_mul_f32 v[118:119], v[118:119], v[198:199]
	v_pk_mul_f32 v[114:115], v[114:115], v[194:195]
	v_pk_mul_f32 v[112:113], v[112:113], v[192:193]
	v_pk_mul_f32 v[108:109], v[108:109], v[204:205]
	v_pk_mul_f32 v[104:105], v[104:105], v[200:201]
	v_pk_mul_f32 v[100:101], v[100:101], v[196:197]
	v_pk_mul_f32 v[110:111], v[110:111], v[206:207]
	v_pk_mul_f32 v[106:107], v[106:107], v[202:203]
	v_pk_mul_f32 v[102:103], v[102:103], v[198:199]
	v_pk_mul_f32 v[98:99], v[98:99], v[194:195]
	v_pk_mul_f32 v[96:97], v[96:97], v[192:193]
	v_pk_mul_f32 v[92:93], v[92:93], v[204:205]
	v_pk_mul_f32 v[88:89], v[88:89], v[200:201]
	v_pk_mul_f32 v[84:85], v[84:85], v[196:197]
	v_pk_mul_f32 v[94:95], v[94:95], v[206:207]
	v_pk_mul_f32 v[90:91], v[90:91], v[202:203]
	v_pk_mul_f32 v[86:87], v[86:87], v[198:199]
	v_pk_mul_f32 v[82:83], v[82:83], v[194:195]
	v_pk_mul_f32 v[80:81], v[80:81], v[192:193]
	v_pk_mul_f32 v[76:77], v[76:77], v[204:205]
	v_pk_mul_f32 v[72:73], v[72:73], v[200:201]
	v_pk_mul_f32 v[68:69], v[68:69], v[196:197]
	v_pk_mul_f32 v[78:79], v[78:79], v[206:207]
	v_pk_mul_f32 v[74:75], v[74:75], v[202:203]
	v_pk_mul_f32 v[70:71], v[70:71], v[198:199]
	v_pk_mul_f32 v[66:67], v[66:67], v[194:195]
	v_pk_mul_f32 v[64:65], v[64:65], v[192:193]
	v_pk_mul_f32 v[60:61], v[60:61], v[204:205]
	v_pk_mul_f32 v[56:57], v[56:57], v[200:201]
	v_pk_mul_f32 v[52:53], v[52:53], v[196:197]
	v_pk_mul_f32 v[62:63], v[62:63], v[206:207]
	v_pk_mul_f32 v[58:59], v[58:59], v[202:203]
	v_pk_mul_f32 v[54:55], v[54:55], v[198:199]
	v_pk_mul_f32 v[50:51], v[50:51], v[194:195]
	v_pk_mul_f32 v[48:49], v[48:49], v[192:193]
	v_pk_mul_f32 v[44:45], v[44:45], v[204:205]
	v_pk_mul_f32 v[40:41], v[40:41], v[200:201]
	v_pk_mul_f32 v[36:37], v[36:37], v[196:197]
	v_pk_mul_f32 v[46:47], v[46:47], v[206:207]
	v_pk_mul_f32 v[42:43], v[42:43], v[202:203]
	v_pk_mul_f32 v[38:39], v[38:39], v[198:199]
	v_pk_mul_f32 v[34:35], v[34:35], v[194:195]
	v_pk_mul_f32 v[32:33], v[32:33], v[192:193]
	v_pk_mul_f32 v[28:29], v[28:29], v[204:205]
	v_pk_mul_f32 v[24:25], v[24:25], v[200:201]
	v_pk_mul_f32 v[20:21], v[20:21], v[196:197]
	v_pk_mul_f32 v[30:31], v[30:31], v[206:207]
	v_pk_mul_f32 v[26:27], v[26:27], v[202:203]
	v_pk_mul_f32 v[22:23], v[22:23], v[198:199]
	v_pk_mul_f32 v[18:19], v[18:19], v[194:195]
	v_pk_mul_f32 v[16:17], v[16:17], v[192:193]
.LBB0_910:
	v_fmamk_f32 v144, v144, 0x3e0293ee, v237
	v_fmamk_f32 v145, v145, 0x3e0293ee, v237
	v_fmamk_f32 v146, v146, 0x3e0293ee, v237
	v_fmamk_f32 v147, v147, 0x3e0293ee, v237
	v_fmamk_f32 v148, v148, 0x3e0293ee, v237
	v_fmamk_f32 v149, v149, 0x3e0293ee, v237
	v_fmamk_f32 v150, v150, 0x3e0293ee, v237
	v_fmamk_f32 v151, v151, 0x3e0293ee, v237
	v_fmamk_f32 v152, v152, 0x3e0293ee, v237
	v_fmamk_f32 v153, v153, 0x3e0293ee, v237
	v_fmamk_f32 v154, v154, 0x3e0293ee, v237
	v_fmamk_f32 v155, v155, 0x3e0293ee, v237
	v_fmamk_f32 v156, v156, 0x3e0293ee, v237
	v_fmamk_f32 v157, v157, 0x3e0293ee, v237
	v_fmamk_f32 v158, v158, 0x3e0293ee, v237
	v_fmamk_f32 v159, v159, 0x3e0293ee, v237
	v_fmamk_f32 v128, v128, 0x3e0293ee, v237
	v_fmamk_f32 v129, v129, 0x3e0293ee, v237
	v_fmamk_f32 v130, v130, 0x3e0293ee, v237
	v_fmamk_f32 v131, v131, 0x3e0293ee, v237
	v_fmamk_f32 v132, v132, 0x3e0293ee, v237
	v_fmamk_f32 v133, v133, 0x3e0293ee, v237
	v_fmamk_f32 v134, v134, 0x3e0293ee, v237
	v_fmamk_f32 v135, v135, 0x3e0293ee, v237
	v_fmamk_f32 v136, v136, 0x3e0293ee, v237
	v_fmamk_f32 v137, v137, 0x3e0293ee, v237
	v_fmamk_f32 v138, v138, 0x3e0293ee, v237
	v_fmamk_f32 v139, v139, 0x3e0293ee, v237
	v_fmamk_f32 v140, v140, 0x3e0293ee, v237
	v_fmamk_f32 v141, v141, 0x3e0293ee, v237
	v_fmamk_f32 v142, v142, 0x3e0293ee, v237
	v_fmamk_f32 v192, v143, 0x3e0293ee, v237
	v_exp_f32_e32 v143, v144
	v_exp_f32_e32 v145, v145
	v_exp_f32_e32 v146, v146
	v_exp_f32_e32 v147, v147
	v_exp_f32_e32 v148, v148
	v_exp_f32_e32 v193, v128
	v_exp_f32_e32 v149, v149
	v_add_f32_e32 v128, v145, v143
	v_exp_f32_e32 v150, v150
	v_add_f32_e32 v128, v146, v128
	v_exp_f32_e32 v151, v151
	v_add_f32_e32 v128, v147, v128
	v_exp_f32_e32 v152, v152
	v_add_f32_e32 v128, v148, v128
	v_exp_f32_e32 v153, v153
	v_add_f32_e32 v128, v149, v128
	v_exp_f32_e32 v154, v154
	v_add_f32_e32 v128, v150, v128
	v_exp_f32_e32 v155, v155
	v_add_f32_e32 v128, v151, v128
	v_exp_f32_e32 v156, v156
	v_add_f32_e32 v128, v152, v128
	v_exp_f32_e32 v157, v157
	v_add_f32_e32 v128, v153, v128
	v_exp_f32_e32 v158, v158
	v_add_f32_e32 v128, v154, v128
	v_exp_f32_e32 v159, v159
	v_add_f32_e32 v128, v155, v128
	v_add_f32_e32 v128, v156, v128
	v_exp_f32_e32 v194, v129
	v_add_f32_e32 v128, v157, v128
	v_exp_f32_e32 v195, v130
	v_add_f32_e32 v128, v158, v128
	v_exp_f32_e32 v196, v131
	v_add_f32_e32 v128, v159, v128
	v_exp_f32_e32 v197, v132
	v_add_f32_e32 v128, v193, v128
	v_exp_f32_e32 v198, v133
	v_add_f32_e32 v128, v194, v128
	v_exp_f32_e32 v199, v134
	v_add_f32_e32 v128, v195, v128
	v_exp_f32_e32 v135, v135
	v_add_f32_e32 v128, v196, v128
	v_exp_f32_e32 v200, v136
	v_add_f32_e32 v128, v197, v128
	v_exp_f32_e32 v201, v137
	v_add_f32_e32 v128, v198, v128
	v_exp_f32_e32 v202, v138
	v_add_f32_e32 v128, v199, v128
	v_exp_f32_e32 v203, v139
	v_add_f32_e32 v128, v135, v128
	v_exp_f32_e32 v204, v140
	v_add_f32_e32 v128, v200, v128
	v_exp_f32_e32 v205, v141
	v_add_f32_e32 v128, v201, v128
	v_exp_f32_e32 v206, v142
	v_add_f32_e32 v128, v202, v128
	v_exp_f32_e32 v192, v192
	v_add_f32_e32 v128, v203, v128
	v_add_f32_e32 v128, v204, v128
	v_add_f32_e32 v128, v205, v128
	v_add_f32_e32 v128, v206, v128
	v_add_f32_e32 v128, v192, v128
	v_add_f32_e32 v232, v232, v128
	v_cvt_pk_bf16_f32 v128, v143, v145
	v_cvt_pk_bf16_f32 v129, v146, v147
	v_cvt_pk_bf16_f32 v130, v148, v149
	v_cvt_pk_bf16_f32 v131, v150, v151
	v_cvt_pk_bf16_f32 v136, v152, v153
	v_cvt_pk_bf16_f32 v137, v154, v155
	v_cvt_pk_bf16_f32 v138, v156, v157
	v_cvt_pk_bf16_f32 v139, v158, v159
	v_cvt_pk_bf16_f32 v132, v193, v194
	v_cvt_pk_bf16_f32 v133, v195, v196
	v_cvt_pk_bf16_f32 v134, v197, v198
	v_cvt_pk_bf16_f32 v135, v199, v135
	v_cvt_pk_bf16_f32 v140, v200, v201
	v_cvt_pk_bf16_f32 v141, v202, v203
	v_cvt_pk_bf16_f32 v142, v204, v205
	v_cvt_pk_bf16_f32 v143, v206, v192
	v_lshl_add_u32 v145, s80, 15, v230
	ds_read_b64_tr_b16 v[146:147], v145 offset:0
	ds_read_b64_tr_b16 v[148:149], v145 offset:4096
	ds_read_b64_tr_b16 v[150:151], v145 offset:512
	ds_read_b64_tr_b16 v[152:153], v145 offset:4608
	ds_read_b64_tr_b16 v[154:155], v145 offset:1024
	ds_read_b64_tr_b16 v[156:157], v145 offset:5120
	ds_read_b64_tr_b16 v[192:193], v145 offset:1536
	ds_read_b64_tr_b16 v[194:195], v145 offset:5632
	ds_read_b64_tr_b16 v[196:197], v145 offset:2048
	ds_read_b64_tr_b16 v[198:199], v145 offset:6144
	ds_read_b64_tr_b16 v[200:201], v145 offset:2560
	ds_read_b64_tr_b16 v[202:203], v145 offset:6656
	ds_read_b64_tr_b16 v[204:205], v145 offset:3072
	ds_read_b64_tr_b16 v[206:207], v145 offset:7168
	s_waitcnt lgkmcnt(12)
	s_nop 0
	v_mfma_f32_32x32x16_bf16 v[0:15], v[128:131], v[146:149], v[0:15]
	ds_read_b64_tr_b16 v[240:241], v145 offset:3584
	ds_read_b64_tr_b16 v[242:243], v145 offset:7680
	s_waitcnt lgkmcnt(12)
	v_mfma_f32_32x32x16_bf16 v[112:127], v[128:131], v[150:153], v[112:127]
	ds_read_b64_tr_b16 v[146:147], v145 offset:8192
	ds_read_b64_tr_b16 v[148:149], v145 offset:12288
	s_waitcnt lgkmcnt(12)
	v_mfma_f32_32x32x16_bf16 v[96:111], v[128:131], v[154:157], v[96:111]
	ds_read_b64_tr_b16 v[150:151], v145 offset:8704
	ds_read_b64_tr_b16 v[152:153], v145 offset:12800
	s_waitcnt lgkmcnt(12)
	v_mfma_f32_32x32x16_bf16 v[80:95], v[128:131], v[192:195], v[80:95]
	ds_read_b64_tr_b16 v[154:155], v145 offset:9216
	ds_read_b64_tr_b16 v[156:157], v145 offset:13312
	s_waitcnt lgkmcnt(12)
	v_mfma_f32_32x32x16_bf16 v[64:79], v[128:131], v[196:199], v[64:79]
	ds_read_b64_tr_b16 v[192:193], v145 offset:9728
	ds_read_b64_tr_b16 v[194:195], v145 offset:13824
	s_waitcnt lgkmcnt(12)
	v_mfma_f32_32x32x16_bf16 v[48:63], v[128:131], v[200:203], v[48:63]
	ds_read_b64_tr_b16 v[196:197], v145 offset:10240
	ds_read_b64_tr_b16 v[198:199], v145 offset:14336
	s_waitcnt lgkmcnt(12)
	v_mfma_f32_32x32x16_bf16 v[32:47], v[128:131], v[204:207], v[32:47]
	ds_read_b64_tr_b16 v[200:201], v145 offset:10752
	ds_read_b64_tr_b16 v[202:203], v145 offset:14848
	s_waitcnt lgkmcnt(12)
	v_mfma_f32_32x32x16_bf16 v[16:31], v[128:131], v[240:243], v[16:31]
	ds_read_b64_tr_b16 v[204:205], v145 offset:11264
	ds_read_b64_tr_b16 v[206:207], v145 offset:15360
	s_waitcnt lgkmcnt(12)
	v_mfma_f32_32x32x16_bf16 v[0:15], v[136:139], v[146:149], v[0:15]
	ds_read_b64_tr_b16 v[240:241], v145 offset:11776
	ds_read_b64_tr_b16 v[242:243], v145 offset:15872
	s_waitcnt lgkmcnt(12)
	v_mfma_f32_32x32x16_bf16 v[112:127], v[136:139], v[150:153], v[112:127]
	ds_read_b64_tr_b16 v[146:147], v145 offset:16384
	ds_read_b64_tr_b16 v[148:149], v145 offset:20480
	s_waitcnt lgkmcnt(12)
	v_mfma_f32_32x32x16_bf16 v[96:111], v[136:139], v[154:157], v[96:111]
	ds_read_b64_tr_b16 v[150:151], v145 offset:16896
	ds_read_b64_tr_b16 v[152:153], v145 offset:20992
	s_waitcnt lgkmcnt(12)
	v_mfma_f32_32x32x16_bf16 v[80:95], v[136:139], v[192:195], v[80:95]
	ds_read_b64_tr_b16 v[154:155], v145 offset:17408
	ds_read_b64_tr_b16 v[156:157], v145 offset:21504
	s_waitcnt lgkmcnt(12)
	v_mfma_f32_32x32x16_bf16 v[64:79], v[136:139], v[196:199], v[64:79]
	ds_read_b64_tr_b16 v[192:193], v145 offset:17920
	ds_read_b64_tr_b16 v[194:195], v145 offset:22016
	s_waitcnt lgkmcnt(12)
	v_mfma_f32_32x32x16_bf16 v[48:63], v[136:139], v[200:203], v[48:63]
	ds_read_b64_tr_b16 v[196:197], v145 offset:18432
	ds_read_b64_tr_b16 v[198:199], v145 offset:22528
	s_waitcnt lgkmcnt(12)
	v_mfma_f32_32x32x16_bf16 v[32:47], v[136:139], v[204:207], v[32:47]
	ds_read_b64_tr_b16 v[200:201], v145 offset:18944
	ds_read_b64_tr_b16 v[202:203], v145 offset:23040
	s_waitcnt lgkmcnt(12)
	v_mfma_f32_32x32x16_bf16 v[16:31], v[136:139], v[240:243], v[16:31]
	ds_read_b64_tr_b16 v[204:205], v145 offset:19456
	ds_read_b64_tr_b16 v[206:207], v145 offset:23552
	s_waitcnt lgkmcnt(12)
	v_mfma_f32_32x32x16_bf16 v[0:15], v[132:135], v[146:149], v[0:15]
	ds_read_b64_tr_b16 v[240:241], v145 offset:19968
	ds_read_b64_tr_b16 v[242:243], v145 offset:24064
	s_waitcnt lgkmcnt(12)
	v_mfma_f32_32x32x16_bf16 v[112:127], v[132:135], v[150:153], v[112:127]
	ds_read_b64_tr_b16 v[146:147], v145 offset:24576
	ds_read_b64_tr_b16 v[148:149], v145 offset:28672
	s_waitcnt lgkmcnt(12)
	v_mfma_f32_32x32x16_bf16 v[96:111], v[132:135], v[154:157], v[96:111]
	ds_read_b64_tr_b16 v[150:151], v145 offset:25088
	ds_read_b64_tr_b16 v[152:153], v145 offset:29184
	s_waitcnt lgkmcnt(12)
	v_mfma_f32_32x32x16_bf16 v[80:95], v[132:135], v[192:195], v[80:95]
	ds_read_b64_tr_b16 v[154:155], v145 offset:25600
	ds_read_b64_tr_b16 v[156:157], v145 offset:29696
	s_waitcnt lgkmcnt(12)
	v_mfma_f32_32x32x16_bf16 v[64:79], v[132:135], v[196:199], v[64:79]
	ds_read_b64_tr_b16 v[192:193], v145 offset:26112
	ds_read_b64_tr_b16 v[194:195], v145 offset:30208
	s_waitcnt lgkmcnt(12)
	v_mfma_f32_32x32x16_bf16 v[48:63], v[132:135], v[200:203], v[48:63]
	ds_read_b64_tr_b16 v[196:197], v145 offset:26624
	ds_read_b64_tr_b16 v[198:199], v145 offset:30720
	s_waitcnt lgkmcnt(12)
	v_mfma_f32_32x32x16_bf16 v[32:47], v[132:135], v[204:207], v[32:47]
	ds_read_b64_tr_b16 v[200:201], v145 offset:27136
	ds_read_b64_tr_b16 v[202:203], v145 offset:31232
	s_waitcnt lgkmcnt(12)
	v_mfma_f32_32x32x16_bf16 v[16:31], v[132:135], v[240:243], v[16:31]
	ds_read_b64_tr_b16 v[204:205], v145 offset:27648
	ds_read_b64_tr_b16 v[206:207], v145 offset:31744
	s_waitcnt lgkmcnt(12)
	v_mfma_f32_32x32x16_bf16 v[0:15], v[140:143], v[146:149], v[0:15]
	ds_read_b64_tr_b16 v[240:241], v145 offset:28160
	ds_read_b64_tr_b16 v[242:243], v145 offset:32256
	s_waitcnt lgkmcnt(12)
	v_mfma_f32_32x32x16_bf16 v[112:127], v[140:143], v[150:153], v[112:127]
	s_waitcnt lgkmcnt(10)
	v_mfma_f32_32x32x16_bf16 v[96:111], v[140:143], v[154:157], v[96:111]
	s_waitcnt lgkmcnt(8)
	v_mfma_f32_32x32x16_bf16 v[80:95], v[140:143], v[192:195], v[80:95]
	s_waitcnt lgkmcnt(6)
	v_mfma_f32_32x32x16_bf16 v[64:79], v[140:143], v[196:199], v[64:79]
	s_add_i32 s4, s80, 1
	s_cmp_lg_u32 s80, 2
	s_cselect_b32 s80, s4, 0
	s_add_i32 s4, s78, 1
	s_cmp_lg_u32 s78, 2
	s_cselect_b32 s78, s4, 0
	s_add_u32 s22, s22, 0x20000
	s_waitcnt lgkmcnt(4)
	v_mfma_f32_32x32x16_bf16 v[48:63], v[140:143], v[200:203], v[48:63]
	s_addc_u32 s23, s23, 0
	s_add_i32 s86, s86, 1
	s_cmp_eq_u32 s22, 0x800000
	s_waitcnt lgkmcnt(2)
	v_mfma_f32_32x32x16_bf16 v[32:47], v[140:143], v[204:207], v[32:47]
	s_waitcnt lgkmcnt(0)
	v_mfma_f32_32x32x16_bf16 v[16:31], v[140:143], v[240:243], v[16:31]
	s_cbranch_scc1 .LBB0_914
	s_cmp_eq_u32 s22, 0x7e0000
	s_mov_b64 s[4:5], -1
	s_cbranch_scc1 .LBB0_903

.LBB0_914:
	v_mov_b32_e32 v129, v232
	s_nop 1
	v_permlane32_swap_b32_e32 v232, v129
	v_add_f32_e32 v232, v232, v129
	s_and_saveexec_b64 s[4:5], s[0:1]
	ds_write_b32 v224, v232
	s_or_b64 exec, exec, s[4:5]
	s_waitcnt lgkmcnt(0)
	v_add_u32_e32 v136, s21, v210
	ds_read_b128 v[128:131], v136
	ds_read_b128 v[132:135], v136 offset:32
	s_ashr_i32 s21, s20, 31
	s_lshl_b64 s[0:1], s[20:21], 12
	ds_read_b128 v[138:141], v136 offset:96
	s_waitcnt lgkmcnt(2)
	v_rcp_f32_e32 v142, v128
	v_rcp_f32_e32 v145, v129
	v_rcp_f32_e32 v152, v130
	v_rcp_f32_e32 v161, v131
	ds_read_b128 v[128:131], v136 offset:64
	s_waitcnt lgkmcnt(2)
	v_rcp_f32_e32 v162, v132
	v_rcp_f32_e32 v163, v133
	v_rcp_f32_e32 v164, v134
	v_rcp_f32_e32 v165, v135
	s_waitcnt lgkmcnt(0)
	v_rcp_f32_e32 v137, v128
	v_rcp_f32_e32 v136, v129
	v_rcp_f32_e32 v135, v130
	v_rcp_f32_e32 v134, v131
	v_rcp_f32_e32 v133, v138
	v_rcp_f32_e32 v132, v139
	v_rcp_f32_e32 v131, v140
	v_rcp_f32_e32 v130, v141
	s_add_u32 s0, s66, s0
	s_addc_u32 s1, s67, s1
	s_mov_b64 s[4:5], -1
	s_andn2_b64 vcc, exec, s[18:19]
	v_lshlrev_b32_e32 v210, 2, v219
	v_lshlrev_b32_e32 v128, 14, v218
	v_lshl_add_u32 v129, v218, 5, v219
	v_lshlrev_b32_e32 v128, 4, v129
	s_mov_b32 s96, s0
	s_mov_b32 s97, s1
	s_cbranch_vccnz .Lepi1_p0
	s_lshl_b64 s[4:5], s[20:21], 11
	s_add_u32 s4, s68, s4
	s_addc_u32 s5, s69, s5
	v_lshlrev_b32_e32 v140, 1, v219
	v_lshl_add_u32 v140, v218, 13, v140
	v_mov_b32_e32 v141, 0
	v_lshl_add_u64 v[146:147], s[4:5], 0, v[140:141]
	s_mov_b64 s[100:101], 0x1000
	s_mov_b64 s[98:99], 0x4000
	global_load_dwordx4 v[166:169], v128, s[96:97]
	s_add_u32 s96, s96, 0x1000
	s_addc_u32 s97, s97, 0
	global_load_dwordx4 v[170:173], v128, s[96:97]
	s_add_u32 s96, s96, 0x1000
	s_addc_u32 s97, s97, 0
	global_load_dwordx4 v[174:177], v128, s[96:97]
	s_add_u32 s96, s96, 0x1000
	s_addc_u32 s97, s97, 0
	global_load_dwordx4 v[178:181], v128, s[96:97]
	s_add_u32 s96, s96, 0x1000
	s_addc_u32 s97, s97, 0
	global_load_dwordx4 v[182:185], v128, s[96:97]
	s_add_u32 s96, s96, 0x1000
	s_addc_u32 s97, s97, 0
	global_load_dwordx4 v[186:189], v128, s[96:97]
	s_add_u32 s96, s96, 0x1000
	s_addc_u32 s97, s97, 0
	global_load_dwordx4 v[190:193], v128, s[96:97]
	s_add_u32 s96, s96, 0x1000
	s_addc_u32 s97, s97, 0
	global_load_dwordx4 v[194:197], v128, s[96:97]
	s_add_u32 s96, s96, 0x1000
	s_addc_u32 s97, s97, 0
	global_load_dwordx4 v[198:201], v128, s[96:97]
	s_add_u32 s96, s96, 0x1000
	s_addc_u32 s97, s97, 0
	global_load_dwordx4 v[202:205], v128, s[96:97]
	s_add_u32 s96, s96, 0x1000
	s_addc_u32 s97, s97, 0
	global_load_dwordx4 v[240:243], v128, s[96:97]
	s_add_u32 s96, s96, 0x1000
	s_addc_u32 s97, s97, 0
	global_load_dwordx4 v[244:247], v128, s[96:97]
	s_add_u32 s96, s96, 0x1000
	s_addc_u32 s97, s97, 0
	global_load_dwordx4 v[248:251], v128, s[96:97]
	s_add_u32 s96, s96, 0x1000
	s_addc_u32 s97, s97, 0
	global_load_dwordx4 v[252:255], v128, s[96:97]
	s_add_u32 s96, s96, 0x1000
	s_addc_u32 s97, s97, 0
	global_load_dwordx4 v[232:235], v128, s[96:97]
	s_add_u32 s96, s96, 0x1000
	s_addc_u32 s97, s97, 0
	global_load_dwordx4 v[154:157], v128, s[96:97]
	s_add_u32 s96, s96, 0x1000
	s_addc_u32 s97, s97, 0
	s_waitcnt vmcnt(8)
	v_lshl_add_u64 v[148:149], v[146:147], 0, s[100:101]
	v_mul_f32_e32 v158, v0, v142
	v_fma_f32 v166, -v209, v158, v166
	v_bfe_u32 v158, v166, 16, 1
	v_add3_u32 v166, v166, v158, s43
	global_store_short_d16_hi v[146:147], v166, off
	v_mul_f32_e32 v159, v1, v145
	v_fma_f32 v167, -v209, v159, v167
	v_bfe_u32 v159, v167, 16, 1
	v_add3_u32 v167, v167, v159, s43
	global_store_short_d16_hi v[146:147], v167, off offset:2048
	v_mul_f32_e32 v160, v2, v152
	v_fma_f32 v168, -v209, v160, v168
	v_bfe_u32 v160, v168, 16, 1
	v_add3_u32 v168, v168, v160, s43
	global_store_short_d16_hi v[148:149], v168, off
	v_mul_f32_e32 v150, v3, v161
	v_fma_f32 v169, -v209, v150, v169
	v_bfe_u32 v150, v169, 16, 1
	v_add3_u32 v169, v169, v150, s43
	global_store_short_d16_hi v[148:149], v169, off offset:2048
	v_mul_f32_e32 v158, v112, v142
	v_fma_f32 v170, -v209, v158, v170
	v_bfe_u32 v158, v170, 16, 1
	v_add3_u32 v170, v170, v158, s43
	global_store_short_d16_hi v[146:147], v170, off offset:64
	v_mul_f32_e32 v159, v113, v145
	v_fma_f32 v171, -v209, v159, v171
	v_bfe_u32 v159, v171, 16, 1
	v_add3_u32 v171, v171, v159, s43
	global_store_short_d16_hi v[146:147], v171, off offset:2112
	v_mul_f32_e32 v160, v114, v152
	v_fma_f32 v172, -v209, v160, v172
	v_bfe_u32 v160, v172, 16, 1
	v_add3_u32 v172, v172, v160, s43
	global_store_short_d16_hi v[148:149], v172, off offset:64
	v_mul_f32_e32 v150, v115, v161
	v_fma_f32 v173, -v209, v150, v173
	v_bfe_u32 v150, v173, 16, 1
	v_add3_u32 v173, v173, v150, s43
	global_store_short_d16_hi v[148:149], v173, off offset:2112
	v_mul_f32_e32 v158, v96, v142
	v_fma_f32 v174, -v209, v158, v174
	v_bfe_u32 v158, v174, 16, 1
	v_add3_u32 v174, v174, v158, s43
	global_store_short_d16_hi v[146:147], v174, off offset:128
	v_mul_f32_e32 v159, v97, v145
	v_fma_f32 v175, -v209, v159, v175
	v_bfe_u32 v159, v175, 16, 1
	v_add3_u32 v175, v175, v159, s43
	global_store_short_d16_hi v[146:147], v175, off offset:2176
	v_mul_f32_e32 v160, v98, v152
	v_fma_f32 v176, -v209, v160, v176
	v_bfe_u32 v160, v176, 16, 1
	v_add3_u32 v176, v176, v160, s43
	global_store_short_d16_hi v[148:149], v176, off offset:128
	v_mul_f32_e32 v150, v99, v161
	v_fma_f32 v177, -v209, v150, v177
	v_bfe_u32 v150, v177, 16, 1
	v_add3_u32 v177, v177, v150, s43
	global_store_short_d16_hi v[148:149], v177, off offset:2176
	v_mul_f32_e32 v158, v80, v142
	v_fma_f32 v178, -v209, v158, v178
	v_bfe_u32 v158, v178, 16, 1
	v_add3_u32 v178, v178, v158, s43
	global_store_short_d16_hi v[146:147], v178, off offset:192
	v_mul_f32_e32 v159, v81, v145
	v_fma_f32 v179, -v209, v159, v179
	v_bfe_u32 v159, v179, 16, 1
	v_add3_u32 v179, v179, v159, s43
	global_store_short_d16_hi v[146:147], v179, off offset:2240
	v_mul_f32_e32 v160, v82, v152
	v_fma_f32 v180, -v209, v160, v180
	v_bfe_u32 v160, v180, 16, 1
	v_add3_u32 v180, v180, v160, s43
	global_store_short_d16_hi v[148:149], v180, off offset:192
	v_mul_f32_e32 v150, v83, v161
	v_fma_f32 v181, -v209, v150, v181
	v_bfe_u32 v150, v181, 16, 1
	v_add3_u32 v181, v181, v150, s43
	global_store_short_d16_hi v[148:149], v181, off offset:2240
	v_mul_f32_e32 v158, v64, v142
	v_fma_f32 v182, -v209, v158, v182
	v_bfe_u32 v158, v182, 16, 1
	v_add3_u32 v182, v182, v158, s43
	global_store_short_d16_hi v[146:147], v182, off offset:256
	v_mul_f32_e32 v159, v65, v145
	v_fma_f32 v183, -v209, v159, v183
	v_bfe_u32 v159, v183, 16, 1
	v_add3_u32 v183, v183, v159, s43
	global_store_short_d16_hi v[146:147], v183, off offset:2304
	v_mul_f32_e32 v160, v66, v152
	v_fma_f32 v184, -v209, v160, v184
	v_bfe_u32 v160, v184, 16, 1
	v_add3_u32 v184, v184, v160, s43
	global_store_short_d16_hi v[148:149], v184, off offset:256
	v_mul_f32_e32 v150, v67, v161
	v_fma_f32 v185, -v209, v150, v185
	v_bfe_u32 v150, v185, 16, 1
	v_add3_u32 v185, v185, v150, s43
	global_store_short_d16_hi v[148:149], v185, off offset:2304
	v_mul_f32_e32 v158, v48, v142
	v_fma_f32 v186, -v209, v158, v186
	v_bfe_u32 v158, v186, 16, 1
	v_add3_u32 v186, v186, v158, s43
	global_store_short_d16_hi v[146:147], v186, off offset:320
	v_mul_f32_e32 v159, v49, v145
	v_fma_f32 v187, -v209, v159, v187
	v_bfe_u32 v159, v187, 16, 1
	v_add3_u32 v187, v187, v159, s43
	global_store_short_d16_hi v[146:147], v187, off offset:2368
	v_mul_f32_e32 v160, v50, v152
	v_fma_f32 v188, -v209, v160, v188
	v_bfe_u32 v160, v188, 16, 1
	v_add3_u32 v188, v188, v160, s43
	global_store_short_d16_hi v[148:149], v188, off offset:320
	v_mul_f32_e32 v150, v51, v161
	v_fma_f32 v189, -v209, v150, v189
	v_bfe_u32 v150, v189, 16, 1
	v_add3_u32 v189, v189, v150, s43
	global_store_short_d16_hi v[148:149], v189, off offset:2368
	v_mul_f32_e32 v158, v32, v142
	v_fma_f32 v190, -v209, v158, v190
	v_bfe_u32 v158, v190, 16, 1
	v_add3_u32 v190, v190, v158, s43
	global_store_short_d16_hi v[146:147], v190, off offset:384
	v_mul_f32_e32 v159, v33, v145
	v_fma_f32 v191, -v209, v159, v191
	v_bfe_u32 v159, v191, 16, 1
	v_add3_u32 v191, v191, v159, s43
	global_store_short_d16_hi v[146:147], v191, off offset:2432
	v_mul_f32_e32 v160, v34, v152
	v_fma_f32 v192, -v209, v160, v192
	v_bfe_u32 v160, v192, 16, 1
	v_add3_u32 v192, v192, v160, s43
	global_store_short_d16_hi v[148:149], v192, off offset:384
	v_mul_f32_e32 v150, v35, v161
	v_fma_f32 v193, -v209, v150, v193
	v_bfe_u32 v150, v193, 16, 1
	v_add3_u32 v193, v193, v150, s43
	global_store_short_d16_hi v[148:149], v193, off offset:2432
	v_mul_f32_e32 v158, v16, v142
	v_fma_f32 v194, -v209, v158, v194
	v_bfe_u32 v158, v194, 16, 1
	v_add3_u32 v194, v194, v158, s43
	global_store_short_d16_hi v[146:147], v194, off offset:448
	v_mul_f32_e32 v159, v17, v145
	v_fma_f32 v195, -v209, v159, v195
	v_bfe_u32 v159, v195, 16, 1
	v_add3_u32 v195, v195, v159, s43
	global_store_short_d16_hi v[146:147], v195, off offset:2496
	v_mul_f32_e32 v160, v18, v152
	v_fma_f32 v196, -v209, v160, v196
	v_bfe_u32 v160, v196, 16, 1
	v_add3_u32 v196, v196, v160, s43
	global_store_short_d16_hi v[148:149], v196, off offset:448
	v_mul_f32_e32 v150, v19, v161
	v_fma_f32 v197, -v209, v150, v197
	v_bfe_u32 v150, v197, 16, 1
	v_add3_u32 v197, v197, v150, s43
	global_store_short_d16_hi v[148:149], v197, off offset:2496
	global_load_dwordx4 v[166:169], v128, s[96:97]
	s_add_u32 s96, s96, 0x1000
	s_addc_u32 s97, s97, 0
	global_load_dwordx4 v[170:173], v128, s[96:97]
	s_add_u32 s96, s96, 0x1000
	s_addc_u32 s97, s97, 0
	global_load_dwordx4 v[174:177], v128, s[96:97]
	s_add_u32 s96, s96, 0x1000
	s_addc_u32 s97, s97, 0
	global_load_dwordx4 v[178:181], v128, s[96:97]
	s_add_u32 s96, s96, 0x1000
	s_addc_u32 s97, s97, 0
	global_load_dwordx4 v[182:185], v128, s[96:97]
	s_add_u32 s96, s96, 0x1000
	s_addc_u32 s97, s97, 0
	global_load_dwordx4 v[186:189], v128, s[96:97]
	s_add_u32 s96, s96, 0x1000
	s_addc_u32 s97, s97, 0
	global_load_dwordx4 v[190:193], v128, s[96:97]
	s_add_u32 s96, s96, 0x1000
	s_addc_u32 s97, s97, 0
	global_load_dwordx4 v[194:197], v128, s[96:97]
	s_add_u32 s96, s96, 0x1000
	s_addc_u32 s97, s97, 0
	v_lshl_add_u64 v[146:147], v[146:147], 0, s[98:99]
	s_waitcnt vmcnt(40)
	v_lshl_add_u64 v[148:149], v[146:147], 0, s[100:101]
	v_mul_f32_e32 v158, v4, v162
	v_fma_f32 v198, -v209, v158, v198
	v_bfe_u32 v158, v198, 16, 1
	v_add3_u32 v198, v198, v158, s43
	global_store_short_d16_hi v[146:147], v198, off
	v_mul_f32_e32 v159, v5, v163
	v_fma_f32 v199, -v209, v159, v199
	v_bfe_u32 v159, v199, 16, 1
	v_add3_u32 v199, v199, v159, s43
	global_store_short_d16_hi v[146:147], v199, off offset:2048
	v_mul_f32_e32 v160, v6, v164
	v_fma_f32 v200, -v209, v160, v200
	v_bfe_u32 v160, v200, 16, 1
	v_add3_u32 v200, v200, v160, s43
	global_store_short_d16_hi v[148:149], v200, off
	v_mul_f32_e32 v150, v7, v165
	v_fma_f32 v201, -v209, v150, v201
	v_bfe_u32 v150, v201, 16, 1
	v_add3_u32 v201, v201, v150, s43
	global_store_short_d16_hi v[148:149], v201, off offset:2048
	v_mul_f32_e32 v158, v116, v162
	v_fma_f32 v202, -v209, v158, v202
	v_bfe_u32 v158, v202, 16, 1
	v_add3_u32 v202, v202, v158, s43
	global_store_short_d16_hi v[146:147], v202, off offset:64
	v_mul_f32_e32 v159, v117, v163
	v_fma_f32 v203, -v209, v159, v203
	v_bfe_u32 v159, v203, 16, 1
	v_add3_u32 v203, v203, v159, s43
	global_store_short_d16_hi v[146:147], v203, off offset:2112
	v_mul_f32_e32 v160, v118, v164
	v_fma_f32 v204, -v209, v160, v204
	v_bfe_u32 v160, v204, 16, 1
	v_add3_u32 v204, v204, v160, s43
	global_store_short_d16_hi v[148:149], v204, off offset:64
	v_mul_f32_e32 v150, v119, v165
	v_fma_f32 v205, -v209, v150, v205
	v_bfe_u32 v150, v205, 16, 1
	v_add3_u32 v205, v205, v150, s43
	global_store_short_d16_hi v[148:149], v205, off offset:2112
	v_mul_f32_e32 v158, v100, v162
	v_fma_f32 v240, -v209, v158, v240
	v_bfe_u32 v158, v240, 16, 1
	v_add3_u32 v240, v240, v158, s43
	global_store_short_d16_hi v[146:147], v240, off offset:128
	v_mul_f32_e32 v159, v101, v163
	v_fma_f32 v241, -v209, v159, v241
	v_bfe_u32 v159, v241, 16, 1
	v_add3_u32 v241, v241, v159, s43
	global_store_short_d16_hi v[146:147], v241, off offset:2176
	v_mul_f32_e32 v160, v102, v164
	v_fma_f32 v242, -v209, v160, v242
	v_bfe_u32 v160, v242, 16, 1
	v_add3_u32 v242, v242, v160, s43
	global_store_short_d16_hi v[148:149], v242, off offset:128
	v_mul_f32_e32 v150, v103, v165
	v_fma_f32 v243, -v209, v150, v243
	v_bfe_u32 v150, v243, 16, 1
	v_add3_u32 v243, v243, v150, s43
	global_store_short_d16_hi v[148:149], v243, off offset:2176
	v_mul_f32_e32 v158, v84, v162
	v_fma_f32 v244, -v209, v158, v244
	v_bfe_u32 v158, v244, 16, 1
	v_add3_u32 v244, v244, v158, s43
	global_store_short_d16_hi v[146:147], v244, off offset:192
	v_mul_f32_e32 v159, v85, v163
	v_fma_f32 v245, -v209, v159, v245
	v_bfe_u32 v159, v245, 16, 1
	v_add3_u32 v245, v245, v159, s43
	global_store_short_d16_hi v[146:147], v245, off offset:2240
	v_mul_f32_e32 v160, v86, v164
	v_fma_f32 v246, -v209, v160, v246
	v_bfe_u32 v160, v246, 16, 1
	v_add3_u32 v246, v246, v160, s43
	global_store_short_d16_hi v[148:149], v246, off offset:192
	v_mul_f32_e32 v150, v87, v165
	v_fma_f32 v247, -v209, v150, v247
	v_bfe_u32 v150, v247, 16, 1
	v_add3_u32 v247, v247, v150, s43
	global_store_short_d16_hi v[148:149], v247, off offset:2240
	v_mul_f32_e32 v158, v68, v162
	v_fma_f32 v248, -v209, v158, v248
	v_bfe_u32 v158, v248, 16, 1
	v_add3_u32 v248, v248, v158, s43
	global_store_short_d16_hi v[146:147], v248, off offset:256
	v_mul_f32_e32 v159, v69, v163
	v_fma_f32 v249, -v209, v159, v249
	v_bfe_u32 v159, v249, 16, 1
	v_add3_u32 v249, v249, v159, s43
	global_store_short_d16_hi v[146:147], v249, off offset:2304
	v_mul_f32_e32 v160, v70, v164
	v_fma_f32 v250, -v209, v160, v250
	v_bfe_u32 v160, v250, 16, 1
	v_add3_u32 v250, v250, v160, s43
	global_store_short_d16_hi v[148:149], v250, off offset:256
	v_mul_f32_e32 v150, v71, v165
	v_fma_f32 v251, -v209, v150, v251
	v_bfe_u32 v150, v251, 16, 1
	v_add3_u32 v251, v251, v150, s43
	global_store_short_d16_hi v[148:149], v251, off offset:2304
	v_mul_f32_e32 v158, v52, v162
	v_fma_f32 v252, -v209, v158, v252
	v_bfe_u32 v158, v252, 16, 1
	v_add3_u32 v252, v252, v158, s43
	global_store_short_d16_hi v[146:147], v252, off offset:320
	v_mul_f32_e32 v159, v53, v163
	v_fma_f32 v253, -v209, v159, v253
	v_bfe_u32 v159, v253, 16, 1
	v_add3_u32 v253, v253, v159, s43
	global_store_short_d16_hi v[146:147], v253, off offset:2368
	v_mul_f32_e32 v160, v54, v164
	v_fma_f32 v254, -v209, v160, v254
	v_bfe_u32 v160, v254, 16, 1
	v_add3_u32 v254, v254, v160, s43
	global_store_short_d16_hi v[148:149], v254, off offset:320
	v_mul_f32_e32 v150, v55, v165
	v_fma_f32 v255, -v209, v150, v255
	v_bfe_u32 v150, v255, 16, 1
	v_add3_u32 v255, v255, v150, s43
	global_store_short_d16_hi v[148:149], v255, off offset:2368
	v_mul_f32_e32 v158, v36, v162
	v_fma_f32 v232, -v209, v158, v232
	v_bfe_u32 v158, v232, 16, 1
	v_add3_u32 v232, v232, v158, s43
	global_store_short_d16_hi v[146:147], v232, off offset:384
	v_mul_f32_e32 v159, v37, v163
	v_fma_f32 v233, -v209, v159, v233
	v_bfe_u32 v159, v233, 16, 1
	v_add3_u32 v233, v233, v159, s43
	global_store_short_d16_hi v[146:147], v233, off offset:2432
	v_mul_f32_e32 v160, v38, v164
	v_fma_f32 v234, -v209, v160, v234
	v_bfe_u32 v160, v234, 16, 1
	v_add3_u32 v234, v234, v160, s43
	global_store_short_d16_hi v[148:149], v234, off offset:384
	v_mul_f32_e32 v150, v39, v165
	v_fma_f32 v235, -v209, v150, v235
	v_bfe_u32 v150, v235, 16, 1
	v_add3_u32 v235, v235, v150, s43
	global_store_short_d16_hi v[148:149], v235, off offset:2432
	v_mul_f32_e32 v158, v20, v162
	v_fma_f32 v154, -v209, v158, v154
	v_bfe_u32 v158, v154, 16, 1
	v_add3_u32 v154, v154, v158, s43
	global_store_short_d16_hi v[146:147], v154, off offset:448
	v_mul_f32_e32 v159, v21, v163
	v_fma_f32 v155, -v209, v159, v155
	v_bfe_u32 v159, v155, 16, 1
	v_add3_u32 v155, v155, v159, s43
	global_store_short_d16_hi v[146:147], v155, off offset:2496
	v_mul_f32_e32 v160, v22, v164
	v_fma_f32 v156, -v209, v160, v156
	v_bfe_u32 v160, v156, 16, 1
	v_add3_u32 v156, v156, v160, s43
	global_store_short_d16_hi v[148:149], v156, off offset:448
	v_mul_f32_e32 v150, v23, v165
	v_fma_f32 v157, -v209, v150, v157
	v_bfe_u32 v150, v157, 16, 1
	v_add3_u32 v157, v157, v150, s43
	global_store_short_d16_hi v[148:149], v157, off offset:2496
	global_load_dwordx4 v[198:201], v128, s[96:97]
	s_add_u32 s96, s96, 0x1000
	s_addc_u32 s97, s97, 0
	global_load_dwordx4 v[202:205], v128, s[96:97]
	s_add_u32 s96, s96, 0x1000
	s_addc_u32 s97, s97, 0
	global_load_dwordx4 v[240:243], v128, s[96:97]
	s_add_u32 s96, s96, 0x1000
	s_addc_u32 s97, s97, 0
	global_load_dwordx4 v[244:247], v128, s[96:97]
	s_add_u32 s96, s96, 0x1000
	s_addc_u32 s97, s97, 0
	global_load_dwordx4 v[248:251], v128, s[96:97]
	s_add_u32 s96, s96, 0x1000
	s_addc_u32 s97, s97, 0
	global_load_dwordx4 v[252:255], v128, s[96:97]
	s_add_u32 s96, s96, 0x1000
	s_addc_u32 s97, s97, 0
	global_load_dwordx4 v[232:235], v128, s[96:97]
	s_add_u32 s96, s96, 0x1000
	s_addc_u32 s97, s97, 0
	global_load_dwordx4 v[154:157], v128, s[96:97]
	s_add_u32 s96, s96, 0x1000
	s_addc_u32 s97, s97, 0
	v_lshl_add_u64 v[146:147], v[146:147], 0, s[98:99]
	s_waitcnt vmcnt(40)
	v_lshl_add_u64 v[148:149], v[146:147], 0, s[100:101]
	v_mul_f32_e32 v158, v8, v137
	v_fma_f32 v166, -v209, v158, v166
	v_bfe_u32 v158, v166, 16, 1
	v_add3_u32 v166, v166, v158, s43
	global_store_short_d16_hi v[146:147], v166, off
	v_mul_f32_e32 v159, v9, v136
	v_fma_f32 v167, -v209, v159, v167
	v_bfe_u32 v159, v167, 16, 1
	v_add3_u32 v167, v167, v159, s43
	global_store_short_d16_hi v[146:147], v167, off offset:2048
	v_mul_f32_e32 v160, v10, v135
	v_fma_f32 v168, -v209, v160, v168
	v_bfe_u32 v160, v168, 16, 1
	v_add3_u32 v168, v168, v160, s43
	global_store_short_d16_hi v[148:149], v168, off
	v_mul_f32_e32 v150, v11, v134
	v_fma_f32 v169, -v209, v150, v169
	v_bfe_u32 v150, v169, 16, 1
	v_add3_u32 v169, v169, v150, s43
	global_store_short_d16_hi v[148:149], v169, off offset:2048
	v_mul_f32_e32 v158, v120, v137
	v_fma_f32 v170, -v209, v158, v170
	v_bfe_u32 v158, v170, 16, 1
	v_add3_u32 v170, v170, v158, s43
	global_store_short_d16_hi v[146:147], v170, off offset:64
	v_mul_f32_e32 v159, v121, v136
	v_fma_f32 v171, -v209, v159, v171
	v_bfe_u32 v159, v171, 16, 1
	v_add3_u32 v171, v171, v159, s43
	global_store_short_d16_hi v[146:147], v171, off offset:2112
	v_mul_f32_e32 v160, v122, v135
	v_fma_f32 v172, -v209, v160, v172
	v_bfe_u32 v160, v172, 16, 1
	v_add3_u32 v172, v172, v160, s43
	global_store_short_d16_hi v[148:149], v172, off offset:64
	v_mul_f32_e32 v150, v123, v134
	v_fma_f32 v173, -v209, v150, v173
	v_bfe_u32 v150, v173, 16, 1
	v_add3_u32 v173, v173, v150, s43
	global_store_short_d16_hi v[148:149], v173, off offset:2112
	v_mul_f32_e32 v158, v104, v137
	v_fma_f32 v174, -v209, v158, v174
	v_bfe_u32 v158, v174, 16, 1
	v_add3_u32 v174, v174, v158, s43
	global_store_short_d16_hi v[146:147], v174, off offset:128
	v_mul_f32_e32 v159, v105, v136
	v_fma_f32 v175, -v209, v159, v175
	v_bfe_u32 v159, v175, 16, 1
	v_add3_u32 v175, v175, v159, s43
	global_store_short_d16_hi v[146:147], v175, off offset:2176
	v_mul_f32_e32 v160, v106, v135
	v_fma_f32 v176, -v209, v160, v176
	v_bfe_u32 v160, v176, 16, 1
	v_add3_u32 v176, v176, v160, s43
	global_store_short_d16_hi v[148:149], v176, off offset:128
	v_mul_f32_e32 v150, v107, v134
	v_fma_f32 v177, -v209, v150, v177
	v_bfe_u32 v150, v177, 16, 1
	v_add3_u32 v177, v177, v150, s43
	global_store_short_d16_hi v[148:149], v177, off offset:2176
	v_mul_f32_e32 v158, v88, v137
	v_fma_f32 v178, -v209, v158, v178
	v_bfe_u32 v158, v178, 16, 1
	v_add3_u32 v178, v178, v158, s43
	global_store_short_d16_hi v[146:147], v178, off offset:192
	v_mul_f32_e32 v159, v89, v136
	v_fma_f32 v179, -v209, v159, v179
	v_bfe_u32 v159, v179, 16, 1
	v_add3_u32 v179, v179, v159, s43
	global_store_short_d16_hi v[146:147], v179, off offset:2240
	v_mul_f32_e32 v160, v90, v135
	v_fma_f32 v180, -v209, v160, v180
	v_bfe_u32 v160, v180, 16, 1
	v_add3_u32 v180, v180, v160, s43
	global_store_short_d16_hi v[148:149], v180, off offset:192
	v_mul_f32_e32 v150, v91, v134
	v_fma_f32 v181, -v209, v150, v181
	v_bfe_u32 v150, v181, 16, 1
	v_add3_u32 v181, v181, v150, s43
	global_store_short_d16_hi v[148:149], v181, off offset:2240
	v_mul_f32_e32 v158, v72, v137
	v_fma_f32 v182, -v209, v158, v182
	v_bfe_u32 v158, v182, 16, 1
	v_add3_u32 v182, v182, v158, s43
	global_store_short_d16_hi v[146:147], v182, off offset:256
	v_mul_f32_e32 v159, v73, v136
	v_fma_f32 v183, -v209, v159, v183
	v_bfe_u32 v159, v183, 16, 1
	v_add3_u32 v183, v183, v159, s43
	global_store_short_d16_hi v[146:147], v183, off offset:2304
	v_mul_f32_e32 v160, v74, v135
	v_fma_f32 v184, -v209, v160, v184
	v_bfe_u32 v160, v184, 16, 1
	v_add3_u32 v184, v184, v160, s43
	global_store_short_d16_hi v[148:149], v184, off offset:256
	v_mul_f32_e32 v150, v75, v134
	v_fma_f32 v185, -v209, v150, v185
	v_bfe_u32 v150, v185, 16, 1
	v_add3_u32 v185, v185, v150, s43
	global_store_short_d16_hi v[148:149], v185, off offset:2304
	v_mul_f32_e32 v158, v56, v137
	v_fma_f32 v186, -v209, v158, v186
	v_bfe_u32 v158, v186, 16, 1
	v_add3_u32 v186, v186, v158, s43
	global_store_short_d16_hi v[146:147], v186, off offset:320
	v_mul_f32_e32 v159, v57, v136
	v_fma_f32 v187, -v209, v159, v187
	v_bfe_u32 v159, v187, 16, 1
	v_add3_u32 v187, v187, v159, s43
	global_store_short_d16_hi v[146:147], v187, off offset:2368
	v_mul_f32_e32 v160, v58, v135
	v_fma_f32 v188, -v209, v160, v188
	v_bfe_u32 v160, v188, 16, 1
	v_add3_u32 v188, v188, v160, s43
	global_store_short_d16_hi v[148:149], v188, off offset:320
	v_mul_f32_e32 v150, v59, v134
	v_fma_f32 v189, -v209, v150, v189
	v_bfe_u32 v150, v189, 16, 1
	v_add3_u32 v189, v189, v150, s43
	global_store_short_d16_hi v[148:149], v189, off offset:2368
	v_mul_f32_e32 v158, v40, v137
	v_fma_f32 v190, -v209, v158, v190
	v_bfe_u32 v158, v190, 16, 1
	v_add3_u32 v190, v190, v158, s43
	global_store_short_d16_hi v[146:147], v190, off offset:384
	v_mul_f32_e32 v159, v41, v136
	v_fma_f32 v191, -v209, v159, v191
	v_bfe_u32 v159, v191, 16, 1
	v_add3_u32 v191, v191, v159, s43
	global_store_short_d16_hi v[146:147], v191, off offset:2432
	v_mul_f32_e32 v160, v42, v135
	v_fma_f32 v192, -v209, v160, v192
	v_bfe_u32 v160, v192, 16, 1
	v_add3_u32 v192, v192, v160, s43
	global_store_short_d16_hi v[148:149], v192, off offset:384
	v_mul_f32_e32 v150, v43, v134
	v_fma_f32 v193, -v209, v150, v193
	v_bfe_u32 v150, v193, 16, 1
	v_add3_u32 v193, v193, v150, s43
	global_store_short_d16_hi v[148:149], v193, off offset:2432
	v_mul_f32_e32 v158, v24, v137
	v_fma_f32 v194, -v209, v158, v194
	v_bfe_u32 v158, v194, 16, 1
	v_add3_u32 v194, v194, v158, s43
	global_store_short_d16_hi v[146:147], v194, off offset:448
	v_mul_f32_e32 v159, v25, v136
	v_fma_f32 v195, -v209, v159, v195
	v_bfe_u32 v159, v195, 16, 1
	v_add3_u32 v195, v195, v159, s43
	global_store_short_d16_hi v[146:147], v195, off offset:2496
	v_mul_f32_e32 v160, v26, v135
	v_fma_f32 v196, -v209, v160, v196
	v_bfe_u32 v160, v196, 16, 1
	v_add3_u32 v196, v196, v160, s43
	global_store_short_d16_hi v[148:149], v196, off offset:448
	v_mul_f32_e32 v150, v27, v134
	v_fma_f32 v197, -v209, v150, v197
	v_bfe_u32 v150, v197, 16, 1
	v_add3_u32 v197, v197, v150, s43
	global_store_short_d16_hi v[148:149], v197, off offset:2496
	v_lshl_add_u64 v[146:147], v[146:147], 0, s[98:99]
	s_waitcnt vmcnt(32)
	v_lshl_add_u64 v[148:149], v[146:147], 0, s[100:101]
	v_mul_f32_e32 v158, v12, v133
	v_fma_f32 v198, -v209, v158, v198
	v_bfe_u32 v158, v198, 16, 1
	v_add3_u32 v198, v198, v158, s43
	global_store_short_d16_hi v[146:147], v198, off
	v_mul_f32_e32 v159, v13, v132
	v_fma_f32 v199, -v209, v159, v199
	v_bfe_u32 v159, v199, 16, 1
	v_add3_u32 v199, v199, v159, s43
	global_store_short_d16_hi v[146:147], v199, off offset:2048
	v_mul_f32_e32 v160, v14, v131
	v_fma_f32 v200, -v209, v160, v200
	v_bfe_u32 v160, v200, 16, 1
	v_add3_u32 v200, v200, v160, s43
	global_store_short_d16_hi v[148:149], v200, off
	v_mul_f32_e32 v150, v15, v130
	v_fma_f32 v201, -v209, v150, v201
	v_bfe_u32 v150, v201, 16, 1
	v_add3_u32 v201, v201, v150, s43
	global_store_short_d16_hi v[148:149], v201, off offset:2048
	v_mul_f32_e32 v158, v124, v133
	v_fma_f32 v202, -v209, v158, v202
	v_bfe_u32 v158, v202, 16, 1
	v_add3_u32 v202, v202, v158, s43
	global_store_short_d16_hi v[146:147], v202, off offset:64
	v_mul_f32_e32 v159, v125, v132
	v_fma_f32 v203, -v209, v159, v203
	v_bfe_u32 v159, v203, 16, 1
	v_add3_u32 v203, v203, v159, s43
	global_store_short_d16_hi v[146:147], v203, off offset:2112
	v_mul_f32_e32 v160, v126, v131
	v_fma_f32 v204, -v209, v160, v204
	v_bfe_u32 v160, v204, 16, 1
	v_add3_u32 v204, v204, v160, s43
	global_store_short_d16_hi v[148:149], v204, off offset:64
	v_mul_f32_e32 v150, v127, v130
	v_fma_f32 v205, -v209, v150, v205
	v_bfe_u32 v150, v205, 16, 1
	v_add3_u32 v205, v205, v150, s43
	global_store_short_d16_hi v[148:149], v205, off offset:2112
	v_mul_f32_e32 v158, v108, v133
	v_fma_f32 v240, -v209, v158, v240
	v_bfe_u32 v158, v240, 16, 1
	v_add3_u32 v240, v240, v158, s43
	global_store_short_d16_hi v[146:147], v240, off offset:128
	v_mul_f32_e32 v159, v109, v132
	v_fma_f32 v241, -v209, v159, v241
	v_bfe_u32 v159, v241, 16, 1
	v_add3_u32 v241, v241, v159, s43
	global_store_short_d16_hi v[146:147], v241, off offset:2176
	v_mul_f32_e32 v160, v110, v131
	v_fma_f32 v242, -v209, v160, v242
	v_bfe_u32 v160, v242, 16, 1
	v_add3_u32 v242, v242, v160, s43
	global_store_short_d16_hi v[148:149], v242, off offset:128
	v_mul_f32_e32 v150, v111, v130
	v_fma_f32 v243, -v209, v150, v243
	v_bfe_u32 v150, v243, 16, 1
	v_add3_u32 v243, v243, v150, s43
	global_store_short_d16_hi v[148:149], v243, off offset:2176
	v_mul_f32_e32 v158, v92, v133
	v_fma_f32 v244, -v209, v158, v244
	v_bfe_u32 v158, v244, 16, 1
	v_add3_u32 v244, v244, v158, s43
	global_store_short_d16_hi v[146:147], v244, off offset:192
	v_mul_f32_e32 v159, v93, v132
	v_fma_f32 v245, -v209, v159, v245
	v_bfe_u32 v159, v245, 16, 1
	v_add3_u32 v245, v245, v159, s43
	global_store_short_d16_hi v[146:147], v245, off offset:2240
	v_mul_f32_e32 v160, v94, v131
	v_fma_f32 v246, -v209, v160, v246
	v_bfe_u32 v160, v246, 16, 1
	v_add3_u32 v246, v246, v160, s43
	global_store_short_d16_hi v[148:149], v246, off offset:192
	v_mul_f32_e32 v150, v95, v130
	v_fma_f32 v247, -v209, v150, v247
	v_bfe_u32 v150, v247, 16, 1
	v_add3_u32 v247, v247, v150, s43
	global_store_short_d16_hi v[148:149], v247, off offset:2240
	v_mul_f32_e32 v158, v76, v133
	v_fma_f32 v248, -v209, v158, v248
	v_bfe_u32 v158, v248, 16, 1
	v_add3_u32 v248, v248, v158, s43
	global_store_short_d16_hi v[146:147], v248, off offset:256
	v_mul_f32_e32 v159, v77, v132
	v_fma_f32 v249, -v209, v159, v249
	v_bfe_u32 v159, v249, 16, 1
	v_add3_u32 v249, v249, v159, s43
	global_store_short_d16_hi v[146:147], v249, off offset:2304
	v_mul_f32_e32 v160, v78, v131
	v_fma_f32 v250, -v209, v160, v250
	v_bfe_u32 v160, v250, 16, 1
	v_add3_u32 v250, v250, v160, s43
	global_store_short_d16_hi v[148:149], v250, off offset:256
	v_mul_f32_e32 v150, v79, v130
	v_fma_f32 v251, -v209, v150, v251
	v_bfe_u32 v150, v251, 16, 1
	v_add3_u32 v251, v251, v150, s43
	global_store_short_d16_hi v[148:149], v251, off offset:2304
	v_mul_f32_e32 v158, v60, v133
	v_fma_f32 v252, -v209, v158, v252
	v_bfe_u32 v158, v252, 16, 1
	v_add3_u32 v252, v252, v158, s43
	global_store_short_d16_hi v[146:147], v252, off offset:320
	v_mul_f32_e32 v159, v61, v132
	v_fma_f32 v253, -v209, v159, v253
	v_bfe_u32 v159, v253, 16, 1
	v_add3_u32 v253, v253, v159, s43
	global_store_short_d16_hi v[146:147], v253, off offset:2368
	v_mul_f32_e32 v160, v62, v131
	v_fma_f32 v254, -v209, v160, v254
	v_bfe_u32 v160, v254, 16, 1
	v_add3_u32 v254, v254, v160, s43
	global_store_short_d16_hi v[148:149], v254, off offset:320
	v_mul_f32_e32 v150, v63, v130
	v_fma_f32 v255, -v209, v150, v255
	v_bfe_u32 v150, v255, 16, 1
	v_add3_u32 v255, v255, v150, s43
	global_store_short_d16_hi v[148:149], v255, off offset:2368
	v_mul_f32_e32 v158, v44, v133
	v_fma_f32 v232, -v209, v158, v232
	v_bfe_u32 v158, v232, 16, 1
	v_add3_u32 v232, v232, v158, s43
	global_store_short_d16_hi v[146:147], v232, off offset:384
	v_mul_f32_e32 v159, v45, v132
	v_fma_f32 v233, -v209, v159, v233
	v_bfe_u32 v159, v233, 16, 1
	v_add3_u32 v233, v233, v159, s43
	global_store_short_d16_hi v[146:147], v233, off offset:2432
	v_mul_f32_e32 v160, v46, v131
	v_fma_f32 v234, -v209, v160, v234
	v_bfe_u32 v160, v234, 16, 1
	v_add3_u32 v234, v234, v160, s43
	global_store_short_d16_hi v[148:149], v234, off offset:384
	v_mul_f32_e32 v150, v47, v130
	v_fma_f32 v235, -v209, v150, v235
	v_bfe_u32 v150, v235, 16, 1
	v_add3_u32 v235, v235, v150, s43
	global_store_short_d16_hi v[148:149], v235, off offset:2432
	v_mul_f32_e32 v158, v28, v133
	v_fma_f32 v154, -v209, v158, v154
	v_bfe_u32 v158, v154, 16, 1
	v_add3_u32 v154, v154, v158, s43
	global_store_short_d16_hi v[146:147], v154, off offset:448
	v_mul_f32_e32 v159, v29, v132
	v_fma_f32 v155, -v209, v159, v155
	v_bfe_u32 v159, v155, 16, 1
	v_add3_u32 v155, v155, v159, s43
	global_store_short_d16_hi v[146:147], v155, off offset:2496
	v_mul_f32_e32 v160, v30, v131
	v_fma_f32 v156, -v209, v160, v156
	v_bfe_u32 v160, v156, 16, 1
	v_add3_u32 v156, v156, v160, s43
	global_store_short_d16_hi v[148:149], v156, off offset:448
	v_mul_f32_e32 v150, v31, v130
	v_fma_f32 v157, -v209, v150, v157
	v_bfe_u32 v150, v157, 16, 1
	v_add3_u32 v157, v157, v150, s43
	global_store_short_d16_hi v[148:149], v157, off offset:2496
	s_branch .LBB0_901
